# GEMM K-loops: LDS-DMA loads use SGPR base + 32-bit VGPR offset (saddr) instead of per-load 64-bit VALU address adds
# speedup vs baseline: 1.0038x; 1.0038x over previous
; #define PG8_STAGE(bufoff, gbase, voff) do { _Pragma("unroll") for (int _i = 0; _i < 2; ++_i) \
;         __builtin_amdgcn_global_load_lds((const unsigned*)((const char*)(gbase) + (voff)[_i]), (LAS unsigned*)(lds + (bufoff) + ldsw + _i * 8192), 16, 0, 0); } while (0)
; #define PG8_LDA(dst, b, h) do { _Pragma("unroll") for (int m = 0; m < 4; ++m) _Pragma("unroll") for (int k = 0; k < 2; ++k) dst[m][k] = *(const LAS bf16x8*)(lds + PG8_SA(b, h) + aoff + m * 2048 + k * 1024); } while (0)
; #define PG8_LDB(dst, b, h) do { _Pragma("unroll") for (int n = 0; n < 2; ++n) _Pragma("unroll") for (int k = 0; k < 2; ++k) dst[n][k] = *(const LAS bf16x8*)(lds + PG8_SB(b, h) + boff + n * 2048 + k * 1024); } while (0)
; #define PG8_MMA(ai, bj, At, Bt) do { __builtin_amdgcn_s_setprio(1); _Pragma("unroll") for (int m = 0; m < 4; ++m) _Pragma("unroll") for (int n = 0; n < 2; ++n) _Pragma("unroll") for (int k = 0; k < 2; ++k) \
;         acc[ai][bj][m][n] = __builtin_amdgcn_mfma_f32_16x16x32_bf16(Bt[n][k], At[m][k], acc[ai][bj][m][n], 0, 0, 0); __builtin_amdgcn_s_setprio(0); } while (0)
; #define PG8_WAIT_V(n) asm volatile("s_waitcnt vmcnt(" #n ")" ::: "memory")
; #define PG8_WAIT_L(n) asm volatile("s_waitcnt lgkmcnt(" #n ")" ::: "memory")
; #define PG8_BAR __builtin_amdgcn_s_barrier()
; #define PG8_SCHED __builtin_amdgcn_sched_barrier(0)
; template <class Epi, class Sched, bool ALIGN_EPI>
; __device__ __forceinline__ void gemm_phase(LAS unsigned char* lds, const GemmDesc g, const Sched& S, const Epi& E) {
;     ...
;             const bool last = (t == nt - 2);
;             const char* a1 = cA + (size_t)(t + 1) * kstep;
;             const char* a2 = last ? nA : cA + (size_t)(t + 2) * kstep; const char* b2 = last ? nB : cB + (size_t)(t + 2) * kstep;
;             const char* a3 = a2 + kstep; const char* b3 = b2 + kstep;
;             PG8_LDB(B0, 0, 0); PG8_LDB(B1, 0, 1); PG8_SCHED; PG8_LDA(At, 0, 0); PG8_STAGE(PG8_SA(1, 1), a1 + hstepA, voffA);
;             PG8_WAIT_V(8); PG8_WAIT_L(0); PG8_BAR; PG8_MMA(0, 0, At, B0); PG8_MMA(0, 1, At, B1); PG8_BAR; PG8_SCHED;
;             PG8_LDA(At, 0, 1); PG8_STAGE(PG8_SB(0, 0), b2, voffB); PG8_STAGE(PG8_SB(0, 1), b2 + hstepB, voffB); PG8_STAGE(PG8_SA(0, 0), a2, voffA);
;             PG8_WAIT_V(8); PG8_WAIT_L(0); PG8_BAR; PG8_MMA(1, 0, At, B0); PG8_MMA(1, 1, At, B1); PG8_BAR; PG8_SCHED;
.LBB0_328:
	ds_read_b128 v[128:131], v169
	ds_read_b128 v[132:135], v169 offset:1024
	ds_read_b128 v[154:157], v169 offset:2048
	ds_read_b128 v[158:161], v169 offset:3072
	ds_read_b128 v[162:165], v170
	ds_read_b128 v[172:175], v170 offset:1024
	ds_read_b128 v[176:179], v170 offset:2048
	ds_read_b128 v[180:183], v170 offset:3072
	s_add_u32 s28, s4, 0xfffc0080
	s_addc_u32 s29, s5, -1
	s_cmp_eq_u32 s63, 12
	s_cselect_b32 s41, s17, s29
	s_cselect_b32 s40, s23, s28
	s_cselect_b32 s29, s25, s62
	s_cselect_b32 s28, s26, s27
	s_add_i32 m0, s64, 0xc000
	ds_read_b128 v[184:187], v171
	ds_read_b128 v[188:191], v171 offset:1024
	ds_read_b128 v[192:195], v171 offset:2048
	ds_read_b128 v[196:199], v171 offset:3072
	ds_read_b128 v[204:207], v171 offset:4096
	ds_read_b128 v[208:211], v171 offset:5120
	ds_read_b128 v[212:215], v171 offset:6144
	ds_read_b128 v[216:219], v171 offset:7168
	global_load_lds_dwordx4 v146, s[4:5]
	s_add_i32 m0, s64, 0xe000
	s_nop 0
	global_load_lds_dwordx4 v148, s[4:5]
	s_waitcnt vmcnt(8)
	s_waitcnt lgkmcnt(0)
	s_barrier
	s_setprio 1
	s_waitcnt lgkmcnt(0)
	v_mfma_f32_16x16x32_bf16 v[124:127], v[128:131], v[184:187], v[124:127]
	v_mfma_f32_16x16x32_bf16 v[120:123], v[154:157], v[184:187], v[120:123]
	v_mfma_f32_16x16x32_bf16 v[108:111], v[128:131], v[192:195], v[108:111]
	v_mfma_f32_16x16x32_bf16 v[104:107], v[154:157], v[192:195], v[104:107]
	v_mfma_f32_16x16x32_bf16 v[92:95], v[128:131], v[204:207], v[92:95]
	v_mfma_f32_16x16x32_bf16 v[88:91], v[154:157], v[204:207], v[88:91]
	v_mfma_f32_16x16x32_bf16 v[76:79], v[128:131], v[212:215], v[76:79]
	v_mfma_f32_16x16x32_bf16 v[72:75], v[154:157], v[212:215], v[72:75]
	v_mfma_f32_16x16x32_bf16 v[124:127], v[132:135], v[188:191], v[124:127]
	v_mfma_f32_16x16x32_bf16 v[120:123], v[158:161], v[188:191], v[120:123]
	v_mfma_f32_16x16x32_bf16 v[108:111], v[132:135], v[196:199], v[108:111]
	v_mfma_f32_16x16x32_bf16 v[104:107], v[158:161], v[196:199], v[104:107]
	v_mfma_f32_16x16x32_bf16 v[92:95], v[132:135], v[208:211], v[92:95]
	v_mfma_f32_16x16x32_bf16 v[88:91], v[158:161], v[208:211], v[88:91]
	v_mfma_f32_16x16x32_bf16 v[76:79], v[132:135], v[216:219], v[76:79]
	v_mfma_f32_16x16x32_bf16 v[72:75], v[158:161], v[216:219], v[72:75]
	s_setprio 0
	s_setprio 1
	v_mfma_f32_16x16x32_bf16 v[116:119], v[162:165], v[184:187], v[116:119]
	v_mfma_f32_16x16x32_bf16 v[112:115], v[176:179], v[184:187], v[112:115]
	v_mfma_f32_16x16x32_bf16 v[100:103], v[162:165], v[192:195], v[100:103]
	v_mfma_f32_16x16x32_bf16 v[96:99], v[176:179], v[192:195], v[96:99]
	v_mfma_f32_16x16x32_bf16 v[84:87], v[162:165], v[204:207], v[84:87]
	v_mfma_f32_16x16x32_bf16 v[80:83], v[176:179], v[204:207], v[80:83]
	v_mfma_f32_16x16x32_bf16 v[68:71], v[162:165], v[212:215], v[68:71]
	v_mfma_f32_16x16x32_bf16 v[64:67], v[176:179], v[212:215], v[64:67]
	v_mfma_f32_16x16x32_bf16 v[116:119], v[172:175], v[188:191], v[116:119]
	v_mfma_f32_16x16x32_bf16 v[112:115], v[180:183], v[188:191], v[112:115]
	v_mfma_f32_16x16x32_bf16 v[100:103], v[172:175], v[196:199], v[100:103]
	v_mfma_f32_16x16x32_bf16 v[96:99], v[180:183], v[196:199], v[96:99]
	v_mfma_f32_16x16x32_bf16 v[84:87], v[172:175], v[208:211], v[84:87]
	v_mfma_f32_16x16x32_bf16 v[80:83], v[180:183], v[208:211], v[80:83]
	v_mfma_f32_16x16x32_bf16 v[68:71], v[172:175], v[216:219], v[68:71]
	v_mfma_f32_16x16x32_bf16 v[64:67], v[180:183], v[216:219], v[64:67]
	s_setprio 0
	s_barrier
	s_add_i32 s88, s76, s3
	s_add_u32 s98, s28, s14
	s_addc_u32 s99, s29, s15
	s_mov_b32 m0, s88
	ds_read_b128 v[184:187], v171 offset:16384
	ds_read_b128 v[188:191], v171 offset:17408
	ds_read_b128 v[192:195], v171 offset:18432
	ds_read_b128 v[196:199], v171 offset:19456
	ds_read_b128 v[204:207], v171 offset:20480
	ds_read_b128 v[208:211], v171 offset:21504
	ds_read_b128 v[212:215], v171 offset:22528
	ds_read_b128 v[216:219], v171 offset:23552
	global_load_lds_dwordx4 v138, s[28:29]
	s_add_i32 m0, s88, 0x2000
	s_add_u32 s88, s28, 0x40000
	s_addc_u32 s89, s29, 0
	s_add_i32 s90, s77, s3
	global_load_lds_dwordx4 v142, s[28:29]
	s_mov_b32 m0, s90
	s_nop 0
	global_load_lds_dwordx4 v138, s[88:89]
	s_add_i32 m0, s90, 0x2000
	s_nop 0
	global_load_lds_dwordx4 v142, s[88:89]
	s_add_u32 s100, s40, s14
	s_addc_u32 s101, s41, s15
	s_mov_b32 m0, s64
	s_nop 0
	global_load_lds_dwordx4 v136, s[40:41]
	s_mov_b32 m0, s65
	s_nop 0
	global_load_lds_dwordx4 v140, s[40:41]
	s_waitcnt vmcnt(8)
	s_waitcnt lgkmcnt(0)
	s_barrier
	s_setprio 1
	s_waitcnt lgkmcnt(0)
	v_mfma_f32_16x16x32_bf16 v[60:63], v[128:131], v[184:187], v[60:63]
	v_mfma_f32_16x16x32_bf16 v[56:59], v[154:157], v[184:187], v[56:59]
	v_mfma_f32_16x16x32_bf16 v[44:47], v[128:131], v[192:195], v[44:47]
	v_mfma_f32_16x16x32_bf16 v[40:43], v[154:157], v[192:195], v[40:43]
	v_mfma_f32_16x16x32_bf16 v[28:31], v[128:131], v[204:207], v[28:31]
	v_mfma_f32_16x16x32_bf16 v[24:27], v[154:157], v[204:207], v[24:27]
	v_mfma_f32_16x16x32_bf16 v[12:15], v[128:131], v[212:215], v[12:15]
	v_mfma_f32_16x16x32_bf16 v[8:11], v[154:157], v[212:215], v[8:11]
	v_mfma_f32_16x16x32_bf16 v[60:63], v[132:135], v[188:191], v[60:63]
	v_mfma_f32_16x16x32_bf16 v[56:59], v[158:161], v[188:191], v[56:59]
	v_mfma_f32_16x16x32_bf16 v[44:47], v[132:135], v[196:199], v[44:47]
	v_mfma_f32_16x16x32_bf16 v[40:43], v[158:161], v[196:199], v[40:43]
	v_mfma_f32_16x16x32_bf16 v[28:31], v[132:135], v[208:211], v[28:31]
	v_mfma_f32_16x16x32_bf16 v[24:27], v[158:161], v[208:211], v[24:27]
	v_mfma_f32_16x16x32_bf16 v[12:15], v[132:135], v[216:219], v[12:15]
	v_mfma_f32_16x16x32_bf16 v[8:11], v[158:161], v[216:219], v[8:11]
	s_setprio 0
	s_setprio 1
	v_mfma_f32_16x16x32_bf16 v[52:55], v[162:165], v[184:187], v[52:55]
	v_mfma_f32_16x16x32_bf16 v[48:51], v[176:179], v[184:187], v[48:51]
	v_mfma_f32_16x16x32_bf16 v[36:39], v[162:165], v[192:195], v[36:39]
	v_mfma_f32_16x16x32_bf16 v[32:35], v[176:179], v[192:195], v[32:35]
	v_mfma_f32_16x16x32_bf16 v[20:23], v[162:165], v[204:207], v[20:23]
	v_mfma_f32_16x16x32_bf16 v[16:19], v[176:179], v[204:207], v[16:19]
	v_mfma_f32_16x16x32_bf16 v[4:7], v[162:165], v[212:215], v[4:7]
	v_mfma_f32_16x16x32_bf16 v[0:3], v[176:179], v[212:215], v[0:3]
	v_mfma_f32_16x16x32_bf16 v[52:55], v[172:175], v[188:191], v[52:55]
	v_mfma_f32_16x16x32_bf16 v[48:51], v[180:183], v[188:191], v[48:51]
	v_mfma_f32_16x16x32_bf16 v[36:39], v[172:175], v[196:199], v[36:39]
	v_mfma_f32_16x16x32_bf16 v[32:35], v[180:183], v[196:199], v[32:35]
	v_mfma_f32_16x16x32_bf16 v[20:23], v[172:175], v[208:211], v[20:23]
	v_mfma_f32_16x16x32_bf16 v[16:19], v[180:183], v[208:211], v[16:19]
	v_mfma_f32_16x16x32_bf16 v[4:7], v[172:175], v[216:219], v[4:7]
	v_mfma_f32_16x16x32_bf16 v[0:3], v[180:183], v[216:219], v[0:3]
	s_setprio 0
	s_barrier
; #define PG8_STAGE(bufoff, gbase, voff) do { _Pragma("unroll") for (int _i = 0; _i < 2; ++_i) \
;         __builtin_amdgcn_global_load_lds((const unsigned*)((const char*)(gbase) + (voff)[_i]), (LAS unsigned*)(lds + (bufoff) + ldsw + _i * 8192), 16, 0, 0); } while (0)
; #define PG8_LDA(dst, b, h) do { _Pragma("unroll") for (int m = 0; m < 4; ++m) _Pragma("unroll") for (int k = 0; k < 2; ++k) dst[m][k] = *(const LAS bf16x8*)(lds + PG8_SA(b, h) + aoff + m * 2048 + k * 1024); } while (0)
; #define PG8_LDB(dst, b, h) do { _Pragma("unroll") for (int n = 0; n < 2; ++n) _Pragma("unroll") for (int k = 0; k < 2; ++k) dst[n][k] = *(const LAS bf16x8*)(lds + PG8_SB(b, h) + boff + n * 2048 + k * 1024); } while (0)
; #define PG8_MMA(ai, bj, At, Bt) do { __builtin_amdgcn_s_setprio(1); _Pragma("unroll") for (int m = 0; m < 4; ++m) _Pragma("unroll") for (int n = 0; n < 2; ++n) _Pragma("unroll") for (int k = 0; k < 2; ++k) \
;         acc[ai][bj][m][n] = __builtin_amdgcn_mfma_f32_16x16x32_bf16(Bt[n][k], At[m][k], acc[ai][bj][m][n], 0, 0, 0); __builtin_amdgcn_s_setprio(0); } while (0)
; #define PG8_WAIT_V(n) asm volatile("s_waitcnt vmcnt(" #n ")" ::: "memory")
; #define PG8_WAIT_L(n) asm volatile("s_waitcnt lgkmcnt(" #n ")" ::: "memory")
; #define PG8_BAR __builtin_amdgcn_s_barrier()
; #define PG8_SCHED __builtin_amdgcn_sched_barrier(0)
; template <class Epi, class Sched, bool ALIGN_EPI>
; __device__ __forceinline__ void gemm_phase(LAS unsigned char* lds, const GemmDesc g, const Sched& S, const Epi& E) {
;     ...
;             PG8_LDB(B0, 1, 0); PG8_LDB(B1, 1, 1); PG8_SCHED; PG8_LDA(At, 1, 0); PG8_STAGE(PG8_SA(0, 1), a2 + hstepA, voffA);
;             PG8_WAIT_V(8); PG8_WAIT_L(0); PG8_BAR; PG8_MMA(0, 0, At, B0); PG8_MMA(0, 1, At, B1); PG8_BAR; PG8_SCHED;
;             PG8_LDA(At, 1, 1); PG8_STAGE(PG8_SB(1, 0), b3, voffB); PG8_STAGE(PG8_SB(1, 1), b3 + hstepB, voffB); PG8_STAGE(PG8_SA(1, 0), a3, voffA);
;             PG8_WAIT_V(8); PG8_WAIT_L(0); PG8_BAR; PG8_MMA(1, 0, At, B0); PG8_MMA(1, 1, At, B1); PG8_BAR; PG8_SCHED;
;         }
	s_add_i32 s88, 0, 0x18000
	v_add_u32_e32 v144, s88, v168
	s_add_i32 s89, 0, 0x1c000
	ds_read_b128 v[128:131], v144
	ds_read_b128 v[132:135], v144 offset:1024
	ds_read_b128 v[154:157], v144 offset:2048
	ds_read_b128 v[158:161], v144 offset:3072
	v_add_u32_e32 v144, s89, v168
	ds_read_b128 v[162:165], v144
	ds_read_b128 v[172:175], v144 offset:1024
	ds_read_b128 v[176:179], v144 offset:2048
	ds_read_b128 v[180:183], v144 offset:3072
	s_add_u32 s40, s40, 0x40000
	s_addc_u32 s41, s41, 0
	s_mov_b32 m0, s68
	ds_read_b128 v[184:187], v171 offset:32768
	ds_read_b128 v[188:191], v171 offset:33792
	ds_read_b128 v[192:195], v171 offset:34816
	ds_read_b128 v[196:199], v171 offset:35840
	ds_read_b128 v[204:207], v171 offset:36864
	ds_read_b128 v[208:211], v171 offset:37888
	ds_read_b128 v[212:215], v171 offset:38912
	ds_read_b128 v[216:219], v171 offset:39936
	global_load_lds_dwordx4 v136, s[40:41]
	s_mov_b32 m0, s69
	s_nop 0
	global_load_lds_dwordx4 v140, s[40:41]
	s_waitcnt vmcnt(8)
	s_waitcnt lgkmcnt(0)
	s_barrier
	s_setprio 1
	s_waitcnt lgkmcnt(0)
	v_mfma_f32_16x16x32_bf16 v[124:127], v[128:131], v[184:187], v[124:127]
	v_mfma_f32_16x16x32_bf16 v[120:123], v[154:157], v[184:187], v[120:123]
	v_mfma_f32_16x16x32_bf16 v[108:111], v[128:131], v[192:195], v[108:111]
	v_mfma_f32_16x16x32_bf16 v[104:107], v[154:157], v[192:195], v[104:107]
	v_mfma_f32_16x16x32_bf16 v[92:95], v[128:131], v[204:207], v[92:95]
	v_mfma_f32_16x16x32_bf16 v[88:91], v[154:157], v[204:207], v[88:91]
	v_mfma_f32_16x16x32_bf16 v[76:79], v[128:131], v[212:215], v[76:79]
	v_mfma_f32_16x16x32_bf16 v[72:75], v[154:157], v[212:215], v[72:75]
	v_mfma_f32_16x16x32_bf16 v[124:127], v[132:135], v[188:191], v[124:127]
	v_mfma_f32_16x16x32_bf16 v[120:123], v[158:161], v[188:191], v[120:123]
	v_mfma_f32_16x16x32_bf16 v[108:111], v[132:135], v[196:199], v[108:111]
	v_mfma_f32_16x16x32_bf16 v[104:107], v[158:161], v[196:199], v[104:107]
	v_mfma_f32_16x16x32_bf16 v[92:95], v[132:135], v[208:211], v[92:95]
	v_mfma_f32_16x16x32_bf16 v[88:91], v[158:161], v[208:211], v[88:91]
	v_mfma_f32_16x16x32_bf16 v[76:79], v[132:135], v[216:219], v[76:79]
	v_mfma_f32_16x16x32_bf16 v[72:75], v[158:161], v[216:219], v[72:75]
	s_setprio 0
	s_setprio 1
	v_mfma_f32_16x16x32_bf16 v[116:119], v[162:165], v[184:187], v[116:119]
	v_mfma_f32_16x16x32_bf16 v[112:115], v[176:179], v[184:187], v[112:115]
	v_mfma_f32_16x16x32_bf16 v[100:103], v[162:165], v[192:195], v[100:103]
	v_mfma_f32_16x16x32_bf16 v[96:99], v[176:179], v[192:195], v[96:99]
	v_mfma_f32_16x16x32_bf16 v[84:87], v[162:165], v[204:207], v[84:87]
	v_mfma_f32_16x16x32_bf16 v[80:83], v[176:179], v[204:207], v[80:83]
	v_mfma_f32_16x16x32_bf16 v[68:71], v[162:165], v[212:215], v[68:71]
	v_mfma_f32_16x16x32_bf16 v[64:67], v[176:179], v[212:215], v[64:67]
	v_mfma_f32_16x16x32_bf16 v[116:119], v[172:175], v[188:191], v[116:119]
	v_mfma_f32_16x16x32_bf16 v[112:115], v[180:183], v[188:191], v[112:115]
	v_mfma_f32_16x16x32_bf16 v[100:103], v[172:175], v[196:199], v[100:103]
	v_mfma_f32_16x16x32_bf16 v[96:99], v[180:183], v[196:199], v[96:99]
	v_mfma_f32_16x16x32_bf16 v[84:87], v[172:175], v[208:211], v[84:87]
	v_mfma_f32_16x16x32_bf16 v[80:83], v[180:183], v[208:211], v[80:83]
	v_mfma_f32_16x16x32_bf16 v[68:71], v[172:175], v[216:219], v[68:71]
	v_mfma_f32_16x16x32_bf16 v[64:67], v[180:183], v[216:219], v[64:67]
	s_setprio 0
	s_barrier
	s_add_i32 s40, s88, s3
	s_mov_b32 m0, s40
	ds_read_b128 v[184:187], v171 offset:49152
	ds_read_b128 v[188:191], v171 offset:50176
	ds_read_b128 v[192:195], v171 offset:51200
	ds_read_b128 v[196:199], v171 offset:52224
	ds_read_b128 v[204:207], v171 offset:53248
	ds_read_b128 v[208:211], v171 offset:54272
	ds_read_b128 v[212:215], v171 offset:55296
	ds_read_b128 v[216:219], v171 offset:56320
	global_load_lds_dwordx4 v138, s[98:99]
	s_add_i32 m0, s40, 0x2000
	s_add_u32 s28, s28, 0x40080
	s_addc_u32 s29, s29, 0
	s_add_i32 s40, s89, s3
	global_load_lds_dwordx4 v142, s[98:99]
	s_mov_b32 m0, s40
	s_nop 0
	global_load_lds_dwordx4 v138, s[28:29]
	s_add_i32 m0, s40, 0x2000
	s_nop 0
	global_load_lds_dwordx4 v142, s[28:29]
	s_mov_b32 m0, s72
	s_nop 0
	global_load_lds_dwordx4 v136, s[100:101]
	s_mov_b32 m0, s73
	s_nop 0
	global_load_lds_dwordx4 v140, s[100:101]
	s_waitcnt vmcnt(8)
	s_waitcnt lgkmcnt(0)
	s_barrier
	s_setprio 1
	s_waitcnt lgkmcnt(0)
	v_mfma_f32_16x16x32_bf16 v[60:63], v[128:131], v[184:187], v[60:63]
	v_mfma_f32_16x16x32_bf16 v[56:59], v[154:157], v[184:187], v[56:59]
	v_mfma_f32_16x16x32_bf16 v[44:47], v[128:131], v[192:195], v[44:47]
	v_mfma_f32_16x16x32_bf16 v[40:43], v[154:157], v[192:195], v[40:43]
	v_mfma_f32_16x16x32_bf16 v[28:31], v[128:131], v[204:207], v[28:31]
	v_mfma_f32_16x16x32_bf16 v[24:27], v[154:157], v[204:207], v[24:27]
	v_mfma_f32_16x16x32_bf16 v[12:15], v[128:131], v[212:215], v[12:15]
	v_mfma_f32_16x16x32_bf16 v[8:11], v[154:157], v[212:215], v[8:11]
	v_mfma_f32_16x16x32_bf16 v[60:63], v[132:135], v[188:191], v[60:63]
	v_mfma_f32_16x16x32_bf16 v[56:59], v[158:161], v[188:191], v[56:59]
	v_mfma_f32_16x16x32_bf16 v[44:47], v[132:135], v[196:199], v[44:47]
	v_mfma_f32_16x16x32_bf16 v[40:43], v[158:161], v[196:199], v[40:43]
	v_mfma_f32_16x16x32_bf16 v[28:31], v[132:135], v[208:211], v[28:31]
	v_mfma_f32_16x16x32_bf16 v[24:27], v[158:161], v[208:211], v[24:27]
	v_mfma_f32_16x16x32_bf16 v[12:15], v[132:135], v[216:219], v[12:15]
	v_mfma_f32_16x16x32_bf16 v[8:11], v[158:161], v[216:219], v[8:11]
	s_setprio 0
	s_setprio 1
	v_mfma_f32_16x16x32_bf16 v[52:55], v[162:165], v[184:187], v[52:55]
	v_mfma_f32_16x16x32_bf16 v[48:51], v[176:179], v[184:187], v[48:51]
	v_mfma_f32_16x16x32_bf16 v[36:39], v[162:165], v[192:195], v[36:39]
	v_mfma_f32_16x16x32_bf16 v[32:35], v[176:179], v[192:195], v[32:35]
	v_mfma_f32_16x16x32_bf16 v[20:23], v[162:165], v[204:207], v[20:23]
	v_mfma_f32_16x16x32_bf16 v[16:19], v[176:179], v[204:207], v[16:19]
	v_mfma_f32_16x16x32_bf16 v[4:7], v[162:165], v[212:215], v[4:7]
	v_mfma_f32_16x16x32_bf16 v[0:3], v[176:179], v[212:215], v[0:3]
	v_mfma_f32_16x16x32_bf16 v[52:55], v[172:175], v[188:191], v[52:55]
	v_mfma_f32_16x16x32_bf16 v[48:51], v[180:183], v[188:191], v[48:51]
	v_mfma_f32_16x16x32_bf16 v[36:39], v[172:175], v[196:199], v[36:39]
	v_mfma_f32_16x16x32_bf16 v[32:35], v[180:183], v[196:199], v[32:35]
	v_mfma_f32_16x16x32_bf16 v[20:23], v[172:175], v[208:211], v[20:23]
	v_mfma_f32_16x16x32_bf16 v[16:19], v[180:183], v[208:211], v[16:19]
	v_mfma_f32_16x16x32_bf16 v[4:7], v[172:175], v[216:219], v[4:7]
	v_mfma_f32_16x16x32_bf16 v[0:3], v[180:183], v[216:219], v[0:3]
	s_setprio 0
	s_barrier
	s_add_i32 s63, s63, 2
	s_add_u32 s4, s4, 0x100
	s_addc_u32 s5, s5, 0
	s_add_u32 s27, s27, 0x100
	s_addc_u32 s62, s62, 0
	s_cmp_gt_u32 s63, 13
	s_cbranch_scc0 .LBB0_328
	s_and_b64 vcc, exec, s[18:19]
	s_cbranch_vccz .LBB0_331
	s_barrier

; #define PG8_STAGE(bufoff, gbase, voff) do { _Pragma("unroll") for (int _i = 0; _i < 2; ++_i) \
;         __builtin_amdgcn_global_load_lds((const unsigned*)((const char*)(gbase) + (voff)[_i]), (LAS unsigned*)(lds + (bufoff) + ldsw + _i * 8192), 16, 0, 0); } while (0)
; #define PG8_LDA(dst, b, h) do { _Pragma("unroll") for (int m = 0; m < 4; ++m) _Pragma("unroll") for (int k = 0; k < 2; ++k) dst[m][k] = *(const LAS bf16x8*)(lds + PG8_SA(b, h) + aoff + m * 2048 + k * 1024); } while (0)
; #define PG8_LDB(dst, b, h) do { _Pragma("unroll") for (int n = 0; n < 2; ++n) _Pragma("unroll") for (int k = 0; k < 2; ++k) dst[n][k] = *(const LAS bf16x8*)(lds + PG8_SB(b, h) + boff + n * 2048 + k * 1024); } while (0)
; #define PG8_MMA(ai, bj, At, Bt) do { __builtin_amdgcn_s_setprio(1); _Pragma("unroll") for (int m = 0; m < 4; ++m) _Pragma("unroll") for (int n = 0; n < 2; ++n) _Pragma("unroll") for (int k = 0; k < 2; ++k) \
;         acc[ai][bj][m][n] = __builtin_amdgcn_mfma_f32_16x16x32_bf16(Bt[n][k], At[m][k], acc[ai][bj][m][n], 0, 0, 0); __builtin_amdgcn_s_setprio(0); } while (0)
; #define PG8_WAIT_V(n) asm volatile("s_waitcnt vmcnt(" #n ")" ::: "memory")
; #define PG8_WAIT_L(n) asm volatile("s_waitcnt lgkmcnt(" #n ")" ::: "memory")
; #define PG8_BAR __builtin_amdgcn_s_barrier()
; #define PG8_SCHED __builtin_amdgcn_sched_barrier(0)
; template <class Epi, class Sched, bool ALIGN_EPI>
; __device__ __forceinline__ void gemm_phase(LAS unsigned char* lds, const GemmDesc g, const Sched& S, const Epi& E) {
;     ...
;             const bool last = (t == nt - 2);
;             const char* a1 = cA + (size_t)(t + 1) * kstep;
;             const char* a2 = last ? nA : cA + (size_t)(t + 2) * kstep; const char* b2 = last ? nB : cB + (size_t)(t + 2) * kstep;
;             const char* a3 = a2 + kstep; const char* b3 = b2 + kstep;
;             PG8_LDB(B0, 0, 0); PG8_LDB(B1, 0, 1); PG8_SCHED; PG8_LDA(At, 0, 0); PG8_STAGE(PG8_SA(1, 1), a1 + hstepA, voffA);
;             PG8_WAIT_V(8); PG8_WAIT_L(0); PG8_BAR; PG8_MMA(0, 0, At, B0); PG8_MMA(0, 1, At, B1); PG8_BAR; PG8_SCHED;
;             PG8_LDA(At, 0, 1); PG8_STAGE(PG8_SB(0, 0), b2, voffB); PG8_STAGE(PG8_SB(0, 1), b2 + hstepB, voffB); PG8_STAGE(PG8_SA(0, 0), a2, voffA);
;             PG8_WAIT_V(8); PG8_WAIT_L(0); PG8_BAR; PG8_MMA(1, 0, At, B0); PG8_MMA(1, 1, At, B1); PG8_BAR; PG8_SCHED;
.LBB0_740:
	ds_read_b128 v[56:59], v167
	ds_read_b128 v[60:63], v167 offset:1024
	ds_read_b128 v[72:75], v167 offset:2048
	ds_read_b128 v[76:79], v167 offset:3072
	ds_read_b128 v[160:163], v168
	ds_read_b128 v[170:173], v168 offset:1024
	ds_read_b128 v[174:177], v168 offset:2048
	ds_read_b128 v[178:181], v168 offset:3072
	s_add_u32 s26, s24, 0xfffe0080
	s_addc_u32 s27, s25, -1
	s_cmp_eq_u32 s69, 4
	s_cselect_b32 s29, s13, s27
	s_cselect_b32 s28, s19, s26
	s_cselect_b32 s27, s15, s68
	s_cselect_b32 s26, s42, s43
	s_add_i32 m0, s23, 0xc000
	ds_read_b128 v[182:185], v169
	ds_read_b128 v[186:189], v169 offset:1024
	ds_read_b128 v[190:193], v169 offset:2048
	ds_read_b128 v[194:197], v169 offset:3072
	ds_read_b128 v[198:201], v169 offset:4096
	ds_read_b128 v[204:207], v169 offset:5120
	ds_read_b128 v[208:211], v169 offset:6144
	ds_read_b128 v[212:215], v169 offset:7168
	global_load_lds_dwordx4 v152, s[24:25]
	s_add_i32 m0, s23, 0xe000
	s_nop 0
	global_load_lds_dwordx4 v154, s[24:25]
	s_waitcnt vmcnt(8)
	s_waitcnt lgkmcnt(0)
	s_barrier
	s_setprio 1
	s_waitcnt lgkmcnt(0)
	v_mfma_f32_16x16x32_bf16 v[140:143], v[56:59], v[182:185], v[140:143]
	v_mfma_f32_16x16x32_bf16 v[136:139], v[72:75], v[182:185], v[136:139]
	v_mfma_f32_16x16x32_bf16 v[128:131], v[56:59], v[190:193], v[128:131]
	v_mfma_f32_16x16x32_bf16 v[124:127], v[72:75], v[190:193], v[124:127]
	v_mfma_f32_16x16x32_bf16 v[108:111], v[56:59], v[198:201], v[108:111]
	v_mfma_f32_16x16x32_bf16 v[104:107], v[72:75], v[198:201], v[104:107]
	v_mfma_f32_16x16x32_bf16 v[92:95], v[56:59], v[208:211], v[92:95]
	v_mfma_f32_16x16x32_bf16 v[88:91], v[72:75], v[208:211], v[88:91]
	v_mfma_f32_16x16x32_bf16 v[140:143], v[60:63], v[186:189], v[140:143]
	v_mfma_f32_16x16x32_bf16 v[136:139], v[76:79], v[186:189], v[136:139]
	v_mfma_f32_16x16x32_bf16 v[128:131], v[60:63], v[194:197], v[128:131]
	v_mfma_f32_16x16x32_bf16 v[124:127], v[76:79], v[194:197], v[124:127]
	v_mfma_f32_16x16x32_bf16 v[108:111], v[60:63], v[204:207], v[108:111]
	v_mfma_f32_16x16x32_bf16 v[104:107], v[76:79], v[204:207], v[104:107]
	v_mfma_f32_16x16x32_bf16 v[92:95], v[60:63], v[212:215], v[92:95]
	v_mfma_f32_16x16x32_bf16 v[88:91], v[76:79], v[212:215], v[88:91]
	s_setprio 0
	s_setprio 1
	v_mfma_f32_16x16x32_bf16 v[132:135], v[160:163], v[182:185], v[132:135]
	v_mfma_f32_16x16x32_bf16 v[120:123], v[174:177], v[182:185], v[120:123]
	v_mfma_f32_16x16x32_bf16 v[116:119], v[160:163], v[190:193], v[116:119]
	v_mfma_f32_16x16x32_bf16 v[112:115], v[174:177], v[190:193], v[112:115]
	v_mfma_f32_16x16x32_bf16 v[100:103], v[160:163], v[198:201], v[100:103]
	v_mfma_f32_16x16x32_bf16 v[96:99], v[174:177], v[198:201], v[96:99]
	v_mfma_f32_16x16x32_bf16 v[84:87], v[160:163], v[208:211], v[84:87]
	v_mfma_f32_16x16x32_bf16 v[80:83], v[174:177], v[208:211], v[80:83]
	v_mfma_f32_16x16x32_bf16 v[132:135], v[170:173], v[186:189], v[132:135]
	v_mfma_f32_16x16x32_bf16 v[120:123], v[178:181], v[186:189], v[120:123]
	v_mfma_f32_16x16x32_bf16 v[116:119], v[170:173], v[194:197], v[116:119]
	v_mfma_f32_16x16x32_bf16 v[112:115], v[178:181], v[194:197], v[112:115]
	v_mfma_f32_16x16x32_bf16 v[100:103], v[170:173], v[204:207], v[100:103]
	v_mfma_f32_16x16x32_bf16 v[96:99], v[178:181], v[204:207], v[96:99]
	v_mfma_f32_16x16x32_bf16 v[84:87], v[170:173], v[212:215], v[84:87]
	v_mfma_f32_16x16x32_bf16 v[80:83], v[178:181], v[212:215], v[80:83]
	s_setprio 0
	s_barrier
	s_add_i32 s70, s66, s31
	s_add_u32 s98, s26, s6
	s_addc_u32 s99, s27, s7
	s_mov_b32 m0, s70
	ds_read_b128 v[182:185], v169 offset:16384
	ds_read_b128 v[186:189], v169 offset:17408
	ds_read_b128 v[190:193], v169 offset:18432
	ds_read_b128 v[194:197], v169 offset:19456
	ds_read_b128 v[198:201], v169 offset:20480
	ds_read_b128 v[204:207], v169 offset:21504
	ds_read_b128 v[208:211], v169 offset:22528
	ds_read_b128 v[212:215], v169 offset:23552
	global_load_lds_dwordx4 v146, s[26:27]
	s_add_i32 m0, s70, 0x2000
	s_add_u32 s70, s26, 0x20000
	s_addc_u32 s71, s27, 0
	s_add_i32 s72, s67, s31
	global_load_lds_dwordx4 v150, s[26:27]
	s_mov_b32 m0, s72
	s_nop 0
	global_load_lds_dwordx4 v146, s[70:71]
	s_add_i32 m0, s72, 0x2000
	s_nop 0
	global_load_lds_dwordx4 v150, s[70:71]
	s_add_u32 s100, s28, s6
	s_addc_u32 s101, s29, s7
	s_mov_b32 m0, s23
	s_nop 0
	global_load_lds_dwordx4 v144, s[28:29]
	s_mov_b32 m0, s34
	s_nop 0
	global_load_lds_dwordx4 v148, s[28:29]
	s_waitcnt vmcnt(8)
	s_waitcnt lgkmcnt(0)
	s_barrier
	s_setprio 1
	s_waitcnt lgkmcnt(0)
	v_mfma_f32_16x16x32_bf16 v[68:71], v[56:59], v[182:185], v[68:71]
	v_mfma_f32_16x16x32_bf16 v[64:67], v[72:75], v[182:185], v[64:67]
	v_mfma_f32_16x16x32_bf16 v[44:47], v[56:59], v[190:193], v[44:47]
	v_mfma_f32_16x16x32_bf16 v[40:43], v[72:75], v[190:193], v[40:43]
	v_mfma_f32_16x16x32_bf16 v[28:31], v[56:59], v[198:201], v[28:31]
	v_mfma_f32_16x16x32_bf16 v[24:27], v[72:75], v[198:201], v[24:27]
	v_mfma_f32_16x16x32_bf16 v[12:15], v[56:59], v[208:211], v[12:15]
	v_mfma_f32_16x16x32_bf16 v[8:11], v[72:75], v[208:211], v[8:11]
	v_mfma_f32_16x16x32_bf16 v[68:71], v[60:63], v[186:189], v[68:71]
	v_mfma_f32_16x16x32_bf16 v[64:67], v[76:79], v[186:189], v[64:67]
	v_mfma_f32_16x16x32_bf16 v[44:47], v[60:63], v[194:197], v[44:47]
	v_mfma_f32_16x16x32_bf16 v[40:43], v[76:79], v[194:197], v[40:43]
	v_mfma_f32_16x16x32_bf16 v[28:31], v[60:63], v[204:207], v[28:31]
	v_mfma_f32_16x16x32_bf16 v[24:27], v[76:79], v[204:207], v[24:27]
	v_mfma_f32_16x16x32_bf16 v[12:15], v[60:63], v[212:215], v[12:15]
	v_mfma_f32_16x16x32_bf16 v[8:11], v[76:79], v[212:215], v[8:11]
	s_setprio 0
	s_setprio 1
	v_mfma_f32_16x16x32_bf16 v[52:55], v[160:163], v[182:185], v[52:55]
	v_mfma_f32_16x16x32_bf16 v[48:51], v[174:177], v[182:185], v[48:51]
	v_mfma_f32_16x16x32_bf16 v[36:39], v[160:163], v[190:193], v[36:39]
	v_mfma_f32_16x16x32_bf16 v[32:35], v[174:177], v[190:193], v[32:35]
	v_mfma_f32_16x16x32_bf16 v[20:23], v[160:163], v[198:201], v[20:23]
	v_mfma_f32_16x16x32_bf16 v[16:19], v[174:177], v[198:201], v[16:19]
	v_mfma_f32_16x16x32_bf16 v[4:7], v[160:163], v[208:211], v[4:7]
	v_mfma_f32_16x16x32_bf16 v[0:3], v[174:177], v[208:211], v[0:3]
	v_mfma_f32_16x16x32_bf16 v[52:55], v[170:173], v[186:189], v[52:55]
	v_mfma_f32_16x16x32_bf16 v[48:51], v[178:181], v[186:189], v[48:51]
	v_mfma_f32_16x16x32_bf16 v[36:39], v[170:173], v[194:197], v[36:39]
	v_mfma_f32_16x16x32_bf16 v[32:35], v[178:181], v[194:197], v[32:35]
	v_mfma_f32_16x16x32_bf16 v[20:23], v[170:173], v[204:207], v[20:23]
	v_mfma_f32_16x16x32_bf16 v[16:19], v[178:181], v[204:207], v[16:19]
	v_mfma_f32_16x16x32_bf16 v[4:7], v[170:173], v[212:215], v[4:7]
	v_mfma_f32_16x16x32_bf16 v[0:3], v[178:181], v[212:215], v[0:3]
	s_setprio 0
	s_barrier
; #define PG8_STAGE(bufoff, gbase, voff) do { _Pragma("unroll") for (int _i = 0; _i < 2; ++_i) \
;         __builtin_amdgcn_global_load_lds((const unsigned*)((const char*)(gbase) + (voff)[_i]), (LAS unsigned*)(lds + (bufoff) + ldsw + _i * 8192), 16, 0, 0); } while (0)
; #define PG8_LDA(dst, b, h) do { _Pragma("unroll") for (int m = 0; m < 4; ++m) _Pragma("unroll") for (int k = 0; k < 2; ++k) dst[m][k] = *(const LAS bf16x8*)(lds + PG8_SA(b, h) + aoff + m * 2048 + k * 1024); } while (0)
; #define PG8_LDB(dst, b, h) do { _Pragma("unroll") for (int n = 0; n < 2; ++n) _Pragma("unroll") for (int k = 0; k < 2; ++k) dst[n][k] = *(const LAS bf16x8*)(lds + PG8_SB(b, h) + boff + n * 2048 + k * 1024); } while (0)
; #define PG8_MMA(ai, bj, At, Bt) do { __builtin_amdgcn_s_setprio(1); _Pragma("unroll") for (int m = 0; m < 4; ++m) _Pragma("unroll") for (int n = 0; n < 2; ++n) _Pragma("unroll") for (int k = 0; k < 2; ++k) \
;         acc[ai][bj][m][n] = __builtin_amdgcn_mfma_f32_16x16x32_bf16(Bt[n][k], At[m][k], acc[ai][bj][m][n], 0, 0, 0); __builtin_amdgcn_s_setprio(0); } while (0)
; #define PG8_WAIT_V(n) asm volatile("s_waitcnt vmcnt(" #n ")" ::: "memory")
; #define PG8_WAIT_L(n) asm volatile("s_waitcnt lgkmcnt(" #n ")" ::: "memory")
; #define PG8_BAR __builtin_amdgcn_s_barrier()
; #define PG8_SCHED __builtin_amdgcn_sched_barrier(0)
; template <class Epi, class Sched, bool ALIGN_EPI>
; __device__ __forceinline__ void gemm_phase(LAS unsigned char* lds, const GemmDesc g, const Sched& S, const Epi& E) {
;     ...
;             PG8_LDB(B0, 1, 0); PG8_LDB(B1, 1, 1); PG8_SCHED; PG8_LDA(At, 1, 0); PG8_STAGE(PG8_SA(0, 1), a2 + hstepA, voffA);
;             PG8_WAIT_V(8); PG8_WAIT_L(0); PG8_BAR; PG8_MMA(0, 0, At, B0); PG8_MMA(0, 1, At, B1); PG8_BAR; PG8_SCHED;
;             PG8_LDA(At, 1, 1); PG8_STAGE(PG8_SB(1, 0), b3, voffB); PG8_STAGE(PG8_SB(1, 1), b3 + hstepB, voffB); PG8_STAGE(PG8_SA(1, 0), a3, voffA);
;             PG8_WAIT_V(8); PG8_WAIT_L(0); PG8_BAR; PG8_MMA(1, 0, At, B0); PG8_MMA(1, 1, At, B1); PG8_BAR; PG8_SCHED;
;         }
	s_add_i32 s70, 0, 0x18000
	s_add_i32 s71, 0, 0x1c000
	v_add_u32_e32 v76, s70, v166
	v_add_u32_e32 v178, s71, v166
	ds_read_b128 v[56:59], v76
	ds_read_b128 v[60:63], v76 offset:1024
	ds_read_b128 v[72:75], v76 offset:2048
	ds_read_b128 v[76:79], v76 offset:3072
	ds_read_b128 v[160:163], v178
	ds_read_b128 v[170:173], v178 offset:1024
	ds_read_b128 v[174:177], v178 offset:2048
	ds_read_b128 v[178:181], v178 offset:3072
	s_add_u32 s28, s28, 0x20000
	s_addc_u32 s29, s29, 0
	s_mov_b32 m0, s35
	ds_read_b128 v[182:185], v169 offset:32768
	ds_read_b128 v[186:189], v169 offset:33792
	ds_read_b128 v[190:193], v169 offset:34816
	ds_read_b128 v[194:197], v169 offset:35840
	ds_read_b128 v[198:201], v169 offset:36864
	ds_read_b128 v[204:207], v169 offset:37888
	ds_read_b128 v[208:211], v169 offset:38912
	ds_read_b128 v[212:215], v169 offset:39936
	global_load_lds_dwordx4 v144, s[28:29]
	s_mov_b32 m0, s36
	s_nop 0
	global_load_lds_dwordx4 v148, s[28:29]
	s_waitcnt vmcnt(8)
	s_waitcnt lgkmcnt(0)
	s_barrier
	s_setprio 1
	s_waitcnt lgkmcnt(0)
	v_mfma_f32_16x16x32_bf16 v[140:143], v[56:59], v[182:185], v[140:143]
	v_mfma_f32_16x16x32_bf16 v[136:139], v[72:75], v[182:185], v[136:139]
	v_mfma_f32_16x16x32_bf16 v[128:131], v[56:59], v[190:193], v[128:131]
	v_mfma_f32_16x16x32_bf16 v[124:127], v[72:75], v[190:193], v[124:127]
	v_mfma_f32_16x16x32_bf16 v[108:111], v[56:59], v[198:201], v[108:111]
	v_mfma_f32_16x16x32_bf16 v[104:107], v[72:75], v[198:201], v[104:107]
	v_mfma_f32_16x16x32_bf16 v[92:95], v[56:59], v[208:211], v[92:95]
	v_mfma_f32_16x16x32_bf16 v[88:91], v[72:75], v[208:211], v[88:91]
	v_mfma_f32_16x16x32_bf16 v[140:143], v[60:63], v[186:189], v[140:143]
	v_mfma_f32_16x16x32_bf16 v[136:139], v[76:79], v[186:189], v[136:139]
	v_mfma_f32_16x16x32_bf16 v[128:131], v[60:63], v[194:197], v[128:131]
	v_mfma_f32_16x16x32_bf16 v[124:127], v[76:79], v[194:197], v[124:127]
	v_mfma_f32_16x16x32_bf16 v[108:111], v[60:63], v[204:207], v[108:111]
	v_mfma_f32_16x16x32_bf16 v[104:107], v[76:79], v[204:207], v[104:107]
	v_mfma_f32_16x16x32_bf16 v[92:95], v[60:63], v[212:215], v[92:95]
	v_mfma_f32_16x16x32_bf16 v[88:91], v[76:79], v[212:215], v[88:91]
	s_setprio 0
	s_setprio 1
	v_mfma_f32_16x16x32_bf16 v[132:135], v[160:163], v[182:185], v[132:135]
	v_mfma_f32_16x16x32_bf16 v[120:123], v[174:177], v[182:185], v[120:123]
	v_mfma_f32_16x16x32_bf16 v[116:119], v[160:163], v[190:193], v[116:119]
	v_mfma_f32_16x16x32_bf16 v[112:115], v[174:177], v[190:193], v[112:115]
	v_mfma_f32_16x16x32_bf16 v[100:103], v[160:163], v[198:201], v[100:103]
	v_mfma_f32_16x16x32_bf16 v[96:99], v[174:177], v[198:201], v[96:99]
	v_mfma_f32_16x16x32_bf16 v[84:87], v[160:163], v[208:211], v[84:87]
	v_mfma_f32_16x16x32_bf16 v[80:83], v[174:177], v[208:211], v[80:83]
	v_mfma_f32_16x16x32_bf16 v[132:135], v[170:173], v[186:189], v[132:135]
	v_mfma_f32_16x16x32_bf16 v[120:123], v[178:181], v[186:189], v[120:123]
	v_mfma_f32_16x16x32_bf16 v[116:119], v[170:173], v[194:197], v[116:119]
	v_mfma_f32_16x16x32_bf16 v[112:115], v[178:181], v[194:197], v[112:115]
	v_mfma_f32_16x16x32_bf16 v[100:103], v[170:173], v[204:207], v[100:103]
	v_mfma_f32_16x16x32_bf16 v[96:99], v[178:181], v[204:207], v[96:99]
	v_mfma_f32_16x16x32_bf16 v[84:87], v[170:173], v[212:215], v[84:87]
	v_mfma_f32_16x16x32_bf16 v[80:83], v[178:181], v[212:215], v[80:83]
	s_setprio 0
	s_barrier
	s_add_i32 s28, s70, s31
	s_mov_b32 m0, s28
	ds_read_b128 v[182:185], v169 offset:49152
	ds_read_b128 v[186:189], v169 offset:50176
	ds_read_b128 v[190:193], v169 offset:51200
	ds_read_b128 v[194:197], v169 offset:52224
	ds_read_b128 v[198:201], v169 offset:53248
	ds_read_b128 v[204:207], v169 offset:54272
	ds_read_b128 v[208:211], v169 offset:55296
	ds_read_b128 v[212:215], v169 offset:56320
	global_load_lds_dwordx4 v146, s[98:99]
	s_add_i32 m0, s28, 0x2000
	s_add_u32 s26, s26, 0x20080
	s_addc_u32 s27, s27, 0
	s_add_i32 s28, s71, s31
	global_load_lds_dwordx4 v150, s[98:99]
	s_mov_b32 m0, s28
	s_nop 0
	global_load_lds_dwordx4 v146, s[26:27]
	s_add_i32 m0, s28, 0x2000
	s_nop 0
	global_load_lds_dwordx4 v150, s[26:27]
	s_mov_b32 m0, s40
	s_nop 0
	global_load_lds_dwordx4 v144, s[100:101]
	s_mov_b32 m0, s41
	s_nop 0
	global_load_lds_dwordx4 v148, s[100:101]
	s_waitcnt vmcnt(8)
	s_waitcnt lgkmcnt(0)
	s_barrier
	s_setprio 1
	s_waitcnt lgkmcnt(0)
	v_mfma_f32_16x16x32_bf16 v[68:71], v[56:59], v[182:185], v[68:71]
	v_mfma_f32_16x16x32_bf16 v[64:67], v[72:75], v[182:185], v[64:67]
	v_mfma_f32_16x16x32_bf16 v[44:47], v[56:59], v[190:193], v[44:47]
	v_mfma_f32_16x16x32_bf16 v[40:43], v[72:75], v[190:193], v[40:43]
	v_mfma_f32_16x16x32_bf16 v[28:31], v[56:59], v[198:201], v[28:31]
	v_mfma_f32_16x16x32_bf16 v[24:27], v[72:75], v[198:201], v[24:27]
	v_mfma_f32_16x16x32_bf16 v[12:15], v[56:59], v[208:211], v[12:15]
	v_mfma_f32_16x16x32_bf16 v[8:11], v[72:75], v[208:211], v[8:11]
	v_mfma_f32_16x16x32_bf16 v[68:71], v[60:63], v[186:189], v[68:71]
	v_mfma_f32_16x16x32_bf16 v[64:67], v[76:79], v[186:189], v[64:67]
	v_mfma_f32_16x16x32_bf16 v[44:47], v[60:63], v[194:197], v[44:47]
	v_mfma_f32_16x16x32_bf16 v[40:43], v[76:79], v[194:197], v[40:43]
	v_mfma_f32_16x16x32_bf16 v[28:31], v[60:63], v[204:207], v[28:31]
	v_mfma_f32_16x16x32_bf16 v[24:27], v[76:79], v[204:207], v[24:27]
	v_mfma_f32_16x16x32_bf16 v[12:15], v[60:63], v[212:215], v[12:15]
	v_mfma_f32_16x16x32_bf16 v[8:11], v[76:79], v[212:215], v[8:11]
	s_setprio 0
	s_setprio 1
	v_mfma_f32_16x16x32_bf16 v[52:55], v[160:163], v[182:185], v[52:55]
	v_mfma_f32_16x16x32_bf16 v[48:51], v[174:177], v[182:185], v[48:51]
	v_mfma_f32_16x16x32_bf16 v[36:39], v[160:163], v[190:193], v[36:39]
	v_mfma_f32_16x16x32_bf16 v[32:35], v[174:177], v[190:193], v[32:35]
	v_mfma_f32_16x16x32_bf16 v[20:23], v[160:163], v[198:201], v[20:23]
	v_mfma_f32_16x16x32_bf16 v[16:19], v[174:177], v[198:201], v[16:19]
	v_mfma_f32_16x16x32_bf16 v[4:7], v[160:163], v[208:211], v[4:7]
	v_mfma_f32_16x16x32_bf16 v[0:3], v[174:177], v[208:211], v[0:3]
	v_mfma_f32_16x16x32_bf16 v[52:55], v[170:173], v[186:189], v[52:55]
	v_mfma_f32_16x16x32_bf16 v[48:51], v[178:181], v[186:189], v[48:51]
	v_mfma_f32_16x16x32_bf16 v[36:39], v[170:173], v[194:197], v[36:39]
	v_mfma_f32_16x16x32_bf16 v[32:35], v[178:181], v[194:197], v[32:35]
	v_mfma_f32_16x16x32_bf16 v[20:23], v[170:173], v[204:207], v[20:23]
	v_mfma_f32_16x16x32_bf16 v[16:19], v[178:181], v[204:207], v[16:19]
	v_mfma_f32_16x16x32_bf16 v[4:7], v[170:173], v[212:215], v[4:7]
	v_mfma_f32_16x16x32_bf16 v[0:3], v[178:181], v[212:215], v[0:3]
	s_setprio 0
	s_barrier
	s_add_i32 s69, s69, 2
	s_add_u32 s24, s24, 0x100
	s_addc_u32 s25, s25, 0
	s_add_u32 s43, s43, 0x100
	s_addc_u32 s68, s68, 0
	s_cmp_gt_u32 s69, 5
	s_cbranch_scc0 .LBB0_740
	s_and_b64 vcc, exec, s[10:11]
	s_cbranch_vccz .LBB0_743
	s_barrier

; #define PG8_STAGE(bufoff, gbase, voff) do { _Pragma("unroll") for (int _i = 0; _i < 2; ++_i) \
;         __builtin_amdgcn_global_load_lds((const unsigned*)((const char*)(gbase) + (voff)[_i]), (LAS unsigned*)(lds + (bufoff) + ldsw + _i * 8192), 16, 0, 0); } while (0)
; #define PG8_LDA(dst, b, h) do { _Pragma("unroll") for (int m = 0; m < 4; ++m) _Pragma("unroll") for (int k = 0; k < 2; ++k) dst[m][k] = *(const LAS bf16x8*)(lds + PG8_SA(b, h) + aoff + m * 2048 + k * 1024); } while (0)
; #define PG8_LDB(dst, b, h) do { _Pragma("unroll") for (int n = 0; n < 2; ++n) _Pragma("unroll") for (int k = 0; k < 2; ++k) dst[n][k] = *(const LAS bf16x8*)(lds + PG8_SB(b, h) + boff + n * 2048 + k * 1024); } while (0)
; #define PG8_MMA(ai, bj, At, Bt) do { __builtin_amdgcn_s_setprio(1); _Pragma("unroll") for (int m = 0; m < 4; ++m) _Pragma("unroll") for (int n = 0; n < 2; ++n) _Pragma("unroll") for (int k = 0; k < 2; ++k) \
;         acc[ai][bj][m][n] = __builtin_amdgcn_mfma_f32_16x16x32_bf16(Bt[n][k], At[m][k], acc[ai][bj][m][n], 0, 0, 0); __builtin_amdgcn_s_setprio(0); } while (0)
; #define PG8_WAIT_V(n) asm volatile("s_waitcnt vmcnt(" #n ")" ::: "memory")
; #define PG8_WAIT_L(n) asm volatile("s_waitcnt lgkmcnt(" #n ")" ::: "memory")
; #define PG8_BAR __builtin_amdgcn_s_barrier()
; #define PG8_SCHED __builtin_amdgcn_sched_barrier(0)
; template <class Epi, class Sched, bool ALIGN_EPI>
; __device__ __forceinline__ void gemm_phase(LAS unsigned char* lds, const GemmDesc g, const Sched& S, const Epi& E) {
;     ...
;             const bool last = (t == nt - 2);
;             const char* a1 = cA + (size_t)(t + 1) * kstep;
;             const char* a2 = last ? nA : cA + (size_t)(t + 2) * kstep; const char* b2 = last ? nB : cB + (size_t)(t + 2) * kstep;
;             const char* a3 = a2 + kstep; const char* b3 = b2 + kstep;
;             PG8_LDB(B0, 0, 0); PG8_LDB(B1, 0, 1); PG8_SCHED; PG8_LDA(At, 0, 0); PG8_STAGE(PG8_SA(1, 1), a1 + hstepA, voffA);
;             PG8_WAIT_V(8); PG8_WAIT_L(0); PG8_BAR; PG8_MMA(0, 0, At, B0); PG8_MMA(0, 1, At, B1); PG8_BAR; PG8_SCHED;
;             PG8_LDA(At, 0, 1); PG8_STAGE(PG8_SB(0, 0), b2, voffB); PG8_STAGE(PG8_SB(0, 1), b2 + hstepB, voffB); PG8_STAGE(PG8_SA(0, 0), a2, voffA);
;             PG8_WAIT_V(8); PG8_WAIT_L(0); PG8_BAR; PG8_MMA(1, 0, At, B0); PG8_MMA(1, 1, At, B1); PG8_BAR; PG8_SCHED;
.LBB0_821:
	ds_read_b128 v[144:147], v153
	ds_read_b128 v[158:161], v153 offset:1024
	ds_read_b128 v[162:165], v153 offset:2048
	ds_read_b128 v[166:169], v153 offset:3072
	ds_read_b128 v[170:173], v154
	ds_read_b128 v[174:177], v154 offset:1024
	ds_read_b128 v[178:181], v154 offset:2048
	ds_read_b128 v[182:185], v154 offset:3072
	s_add_u32 s38, s36, 0xfffc0080
	s_addc_u32 s39, s37, -1
	s_cmp_eq_u32 s72, 12
	s_cselect_b32 s41, s1, s39
	s_cselect_b32 s40, s10, s38
	s_cselect_b32 s39, s21, s71
	s_cselect_b32 s38, s27, s29
	s_add_i32 m0, s25, 0xc000
	ds_read_b128 v[186:189], v155
	ds_read_b128 v[190:193], v155 offset:1024
	ds_read_b128 v[194:197], v155 offset:2048
	ds_read_b128 v[198:201], v155 offset:3072
	ds_read_b128 v[204:207], v155 offset:4096
	ds_read_b128 v[208:211], v155 offset:5120
	ds_read_b128 v[212:215], v155 offset:6144
	ds_read_b128 v[216:219], v155 offset:7168
	global_load_lds_dwordx4 v136, s[36:37]
	s_add_i32 m0, s25, 0xe000
	s_nop 0
	global_load_lds_dwordx4 v138, s[36:37]
	s_waitcnt vmcnt(8)
	s_waitcnt lgkmcnt(0)
	s_barrier
	s_setprio 1
	s_waitcnt lgkmcnt(0)
	v_mfma_f32_16x16x32_bf16 v[124:127], v[144:147], v[186:189], v[124:127]
	v_mfma_f32_16x16x32_bf16 v[120:123], v[162:165], v[186:189], v[120:123]
	v_mfma_f32_16x16x32_bf16 v[108:111], v[144:147], v[194:197], v[108:111]
	v_mfma_f32_16x16x32_bf16 v[104:107], v[162:165], v[194:197], v[104:107]
	v_mfma_f32_16x16x32_bf16 v[92:95], v[144:147], v[204:207], v[92:95]
	v_mfma_f32_16x16x32_bf16 v[88:91], v[162:165], v[204:207], v[88:91]
	v_mfma_f32_16x16x32_bf16 v[76:79], v[144:147], v[212:215], v[76:79]
	v_mfma_f32_16x16x32_bf16 v[72:75], v[162:165], v[212:215], v[72:75]
	v_mfma_f32_16x16x32_bf16 v[124:127], v[158:161], v[190:193], v[124:127]
	v_mfma_f32_16x16x32_bf16 v[120:123], v[166:169], v[190:193], v[120:123]
	v_mfma_f32_16x16x32_bf16 v[108:111], v[158:161], v[198:201], v[108:111]
	v_mfma_f32_16x16x32_bf16 v[104:107], v[166:169], v[198:201], v[104:107]
	v_mfma_f32_16x16x32_bf16 v[92:95], v[158:161], v[208:211], v[92:95]
	v_mfma_f32_16x16x32_bf16 v[88:91], v[166:169], v[208:211], v[88:91]
	v_mfma_f32_16x16x32_bf16 v[76:79], v[158:161], v[216:219], v[76:79]
	v_mfma_f32_16x16x32_bf16 v[72:75], v[166:169], v[216:219], v[72:75]
	s_setprio 0
	s_setprio 1
	v_mfma_f32_16x16x32_bf16 v[116:119], v[170:173], v[186:189], v[116:119]
	v_mfma_f32_16x16x32_bf16 v[112:115], v[178:181], v[186:189], v[112:115]
	v_mfma_f32_16x16x32_bf16 v[100:103], v[170:173], v[194:197], v[100:103]
	v_mfma_f32_16x16x32_bf16 v[96:99], v[178:181], v[194:197], v[96:99]
	v_mfma_f32_16x16x32_bf16 v[84:87], v[170:173], v[204:207], v[84:87]
	v_mfma_f32_16x16x32_bf16 v[80:83], v[178:181], v[204:207], v[80:83]
	v_mfma_f32_16x16x32_bf16 v[68:71], v[170:173], v[212:215], v[68:71]
	v_mfma_f32_16x16x32_bf16 v[64:67], v[178:181], v[212:215], v[64:67]
	v_mfma_f32_16x16x32_bf16 v[116:119], v[174:177], v[190:193], v[116:119]
	v_mfma_f32_16x16x32_bf16 v[112:115], v[182:185], v[190:193], v[112:115]
	v_mfma_f32_16x16x32_bf16 v[100:103], v[174:177], v[198:201], v[100:103]
	v_mfma_f32_16x16x32_bf16 v[96:99], v[182:185], v[198:201], v[96:99]
	v_mfma_f32_16x16x32_bf16 v[84:87], v[174:177], v[208:211], v[84:87]
	v_mfma_f32_16x16x32_bf16 v[80:83], v[182:185], v[208:211], v[80:83]
	v_mfma_f32_16x16x32_bf16 v[68:71], v[174:177], v[216:219], v[68:71]
	v_mfma_f32_16x16x32_bf16 v[64:67], v[182:185], v[216:219], v[64:67]
	s_setprio 0
	s_barrier
	s_add_i32 s73, s68, s3
	s_add_u32 s98, s38, s18
	s_addc_u32 s99, s39, s19
	s_mov_b32 m0, s73
	ds_read_b128 v[186:189], v155 offset:16384
	ds_read_b128 v[190:193], v155 offset:17408
	ds_read_b128 v[194:197], v155 offset:18432
	ds_read_b128 v[198:201], v155 offset:19456
	ds_read_b128 v[204:207], v155 offset:20480
	ds_read_b128 v[208:211], v155 offset:21504
	ds_read_b128 v[212:215], v155 offset:22528
	ds_read_b128 v[216:219], v155 offset:23552
	global_load_lds_dwordx4 v130, s[38:39]
	s_add_i32 m0, s73, 0x2000
	s_add_u32 s80, s38, 0x40000
	s_addc_u32 s81, s39, 0
	s_add_i32 s73, s69, s3
	global_load_lds_dwordx4 v134, s[38:39]
	s_mov_b32 m0, s73
	s_nop 0
	global_load_lds_dwordx4 v130, s[80:81]
	s_add_i32 m0, s73, 0x2000
	s_nop 0
	global_load_lds_dwordx4 v134, s[80:81]
	s_add_u32 s100, s40, s18
	s_addc_u32 s101, s41, s19
	s_mov_b32 m0, s25
	s_nop 0
	global_load_lds_dwordx4 v128, s[40:41]
	s_mov_b32 m0, s4
	s_nop 0
	global_load_lds_dwordx4 v132, s[40:41]
	s_waitcnt vmcnt(8)
	s_waitcnt lgkmcnt(0)
	s_barrier
	s_setprio 1
	s_waitcnt lgkmcnt(0)
	v_mfma_f32_16x16x32_bf16 v[60:63], v[144:147], v[186:189], v[60:63]
	v_mfma_f32_16x16x32_bf16 v[56:59], v[162:165], v[186:189], v[56:59]
	v_mfma_f32_16x16x32_bf16 v[44:47], v[144:147], v[194:197], v[44:47]
	v_mfma_f32_16x16x32_bf16 v[40:43], v[162:165], v[194:197], v[40:43]
	v_mfma_f32_16x16x32_bf16 v[28:31], v[144:147], v[204:207], v[28:31]
	v_mfma_f32_16x16x32_bf16 v[24:27], v[162:165], v[204:207], v[24:27]
	v_mfma_f32_16x16x32_bf16 v[12:15], v[144:147], v[212:215], v[12:15]
	v_mfma_f32_16x16x32_bf16 v[8:11], v[162:165], v[212:215], v[8:11]
	v_mfma_f32_16x16x32_bf16 v[60:63], v[158:161], v[190:193], v[60:63]
	v_mfma_f32_16x16x32_bf16 v[56:59], v[166:169], v[190:193], v[56:59]
	v_mfma_f32_16x16x32_bf16 v[44:47], v[158:161], v[198:201], v[44:47]
	v_mfma_f32_16x16x32_bf16 v[40:43], v[166:169], v[198:201], v[40:43]
	v_mfma_f32_16x16x32_bf16 v[28:31], v[158:161], v[208:211], v[28:31]
	v_mfma_f32_16x16x32_bf16 v[24:27], v[166:169], v[208:211], v[24:27]
	v_mfma_f32_16x16x32_bf16 v[12:15], v[158:161], v[216:219], v[12:15]
	v_mfma_f32_16x16x32_bf16 v[8:11], v[166:169], v[216:219], v[8:11]
	s_setprio 0
	s_setprio 1
	v_mfma_f32_16x16x32_bf16 v[52:55], v[170:173], v[186:189], v[52:55]
	v_mfma_f32_16x16x32_bf16 v[48:51], v[178:181], v[186:189], v[48:51]
	v_mfma_f32_16x16x32_bf16 v[36:39], v[170:173], v[194:197], v[36:39]
	v_mfma_f32_16x16x32_bf16 v[32:35], v[178:181], v[194:197], v[32:35]
	v_mfma_f32_16x16x32_bf16 v[20:23], v[170:173], v[204:207], v[20:23]
	v_mfma_f32_16x16x32_bf16 v[16:19], v[178:181], v[204:207], v[16:19]
	v_mfma_f32_16x16x32_bf16 v[4:7], v[170:173], v[212:215], v[4:7]
	v_mfma_f32_16x16x32_bf16 v[0:3], v[178:181], v[212:215], v[0:3]
	v_mfma_f32_16x16x32_bf16 v[52:55], v[174:177], v[190:193], v[52:55]
	v_mfma_f32_16x16x32_bf16 v[48:51], v[182:185], v[190:193], v[48:51]
	v_mfma_f32_16x16x32_bf16 v[36:39], v[174:177], v[198:201], v[36:39]
	v_mfma_f32_16x16x32_bf16 v[32:35], v[182:185], v[198:201], v[32:35]
	v_mfma_f32_16x16x32_bf16 v[20:23], v[174:177], v[208:211], v[20:23]
	v_mfma_f32_16x16x32_bf16 v[16:19], v[182:185], v[208:211], v[16:19]
	v_mfma_f32_16x16x32_bf16 v[4:7], v[174:177], v[216:219], v[4:7]
	v_mfma_f32_16x16x32_bf16 v[0:3], v[182:185], v[216:219], v[0:3]
	s_setprio 0
	s_barrier
; #define PG8_STAGE(bufoff, gbase, voff) do { _Pragma("unroll") for (int _i = 0; _i < 2; ++_i) \
;         __builtin_amdgcn_global_load_lds((const unsigned*)((const char*)(gbase) + (voff)[_i]), (LAS unsigned*)(lds + (bufoff) + ldsw + _i * 8192), 16, 0, 0); } while (0)
; #define PG8_LDA(dst, b, h) do { _Pragma("unroll") for (int m = 0; m < 4; ++m) _Pragma("unroll") for (int k = 0; k < 2; ++k) dst[m][k] = *(const LAS bf16x8*)(lds + PG8_SA(b, h) + aoff + m * 2048 + k * 1024); } while (0)
; #define PG8_LDB(dst, b, h) do { _Pragma("unroll") for (int n = 0; n < 2; ++n) _Pragma("unroll") for (int k = 0; k < 2; ++k) dst[n][k] = *(const LAS bf16x8*)(lds + PG8_SB(b, h) + boff + n * 2048 + k * 1024); } while (0)
; #define PG8_MMA(ai, bj, At, Bt) do { __builtin_amdgcn_s_setprio(1); _Pragma("unroll") for (int m = 0; m < 4; ++m) _Pragma("unroll") for (int n = 0; n < 2; ++n) _Pragma("unroll") for (int k = 0; k < 2; ++k) \
;         acc[ai][bj][m][n] = __builtin_amdgcn_mfma_f32_16x16x32_bf16(Bt[n][k], At[m][k], acc[ai][bj][m][n], 0, 0, 0); __builtin_amdgcn_s_setprio(0); } while (0)
; #define PG8_WAIT_V(n) asm volatile("s_waitcnt vmcnt(" #n ")" ::: "memory")
; #define PG8_WAIT_L(n) asm volatile("s_waitcnt lgkmcnt(" #n ")" ::: "memory")
; #define PG8_BAR __builtin_amdgcn_s_barrier()
; #define PG8_SCHED __builtin_amdgcn_sched_barrier(0)
; template <class Epi, class Sched, bool ALIGN_EPI>
; __device__ __forceinline__ void gemm_phase(LAS unsigned char* lds, const GemmDesc g, const Sched& S, const Epi& E) {
;     ...
;             PG8_LDB(B0, 1, 0); PG8_LDB(B1, 1, 1); PG8_SCHED; PG8_LDA(At, 1, 0); PG8_STAGE(PG8_SA(0, 1), a2 + hstepA, voffA);
;             PG8_WAIT_V(8); PG8_WAIT_L(0); PG8_BAR; PG8_MMA(0, 0, At, B0); PG8_MMA(0, 1, At, B1); PG8_BAR; PG8_SCHED;
;             PG8_LDA(At, 1, 1); PG8_STAGE(PG8_SB(1, 0), b3, voffB); PG8_STAGE(PG8_SB(1, 1), b3 + hstepB, voffB); PG8_STAGE(PG8_SA(1, 0), a3, voffA);
;             PG8_WAIT_V(8); PG8_WAIT_L(0); PG8_BAR; PG8_MMA(1, 0, At, B0); PG8_MMA(1, 1, At, B1); PG8_BAR; PG8_SCHED;
;         }
	s_add_i32 s73, 0, 0x18000
	v_add_u32_e32 v157, s73, v152
	s_add_i32 s79, 0, 0x1c000
	ds_read_b128 v[144:147], v157
	ds_read_b128 v[158:161], v157 offset:1024
	ds_read_b128 v[162:165], v157 offset:2048
	ds_read_b128 v[166:169], v157 offset:3072
	v_add_u32_e32 v157, s79, v152
	ds_read_b128 v[170:173], v157
	ds_read_b128 v[174:177], v157 offset:1024
	ds_read_b128 v[178:181], v157 offset:2048
	ds_read_b128 v[182:185], v157 offset:3072
	s_add_u32 s40, s40, 0x40000
	s_addc_u32 s41, s41, 0
	s_mov_b32 m0, s5
	ds_read_b128 v[186:189], v155 offset:32768
	ds_read_b128 v[190:193], v155 offset:33792
	ds_read_b128 v[194:197], v155 offset:34816
	ds_read_b128 v[198:201], v155 offset:35840
	ds_read_b128 v[204:207], v155 offset:36864
	ds_read_b128 v[208:211], v155 offset:37888
	ds_read_b128 v[212:215], v155 offset:38912
	ds_read_b128 v[216:219], v155 offset:39936
	global_load_lds_dwordx4 v128, s[40:41]
	s_mov_b32 m0, s42
	s_nop 0
	global_load_lds_dwordx4 v132, s[40:41]
	s_waitcnt vmcnt(8)
	s_waitcnt lgkmcnt(0)
	s_barrier
	s_setprio 1
	s_waitcnt lgkmcnt(0)
	v_mfma_f32_16x16x32_bf16 v[124:127], v[144:147], v[186:189], v[124:127]
	v_mfma_f32_16x16x32_bf16 v[120:123], v[162:165], v[186:189], v[120:123]
	v_mfma_f32_16x16x32_bf16 v[108:111], v[144:147], v[194:197], v[108:111]
	v_mfma_f32_16x16x32_bf16 v[104:107], v[162:165], v[194:197], v[104:107]
	v_mfma_f32_16x16x32_bf16 v[92:95], v[144:147], v[204:207], v[92:95]
	v_mfma_f32_16x16x32_bf16 v[88:91], v[162:165], v[204:207], v[88:91]
	v_mfma_f32_16x16x32_bf16 v[76:79], v[144:147], v[212:215], v[76:79]
	v_mfma_f32_16x16x32_bf16 v[72:75], v[162:165], v[212:215], v[72:75]
	v_mfma_f32_16x16x32_bf16 v[124:127], v[158:161], v[190:193], v[124:127]
	v_mfma_f32_16x16x32_bf16 v[120:123], v[166:169], v[190:193], v[120:123]
	v_mfma_f32_16x16x32_bf16 v[108:111], v[158:161], v[198:201], v[108:111]
	v_mfma_f32_16x16x32_bf16 v[104:107], v[166:169], v[198:201], v[104:107]
	v_mfma_f32_16x16x32_bf16 v[92:95], v[158:161], v[208:211], v[92:95]
	v_mfma_f32_16x16x32_bf16 v[88:91], v[166:169], v[208:211], v[88:91]
	v_mfma_f32_16x16x32_bf16 v[76:79], v[158:161], v[216:219], v[76:79]
	v_mfma_f32_16x16x32_bf16 v[72:75], v[166:169], v[216:219], v[72:75]
	s_setprio 0
	s_setprio 1
	v_mfma_f32_16x16x32_bf16 v[116:119], v[170:173], v[186:189], v[116:119]
	v_mfma_f32_16x16x32_bf16 v[112:115], v[178:181], v[186:189], v[112:115]
	v_mfma_f32_16x16x32_bf16 v[100:103], v[170:173], v[194:197], v[100:103]
	v_mfma_f32_16x16x32_bf16 v[96:99], v[178:181], v[194:197], v[96:99]
	v_mfma_f32_16x16x32_bf16 v[84:87], v[170:173], v[204:207], v[84:87]
	v_mfma_f32_16x16x32_bf16 v[80:83], v[178:181], v[204:207], v[80:83]
	v_mfma_f32_16x16x32_bf16 v[68:71], v[170:173], v[212:215], v[68:71]
	v_mfma_f32_16x16x32_bf16 v[64:67], v[178:181], v[212:215], v[64:67]
	v_mfma_f32_16x16x32_bf16 v[116:119], v[174:177], v[190:193], v[116:119]
	v_mfma_f32_16x16x32_bf16 v[112:115], v[182:185], v[190:193], v[112:115]
	v_mfma_f32_16x16x32_bf16 v[100:103], v[174:177], v[198:201], v[100:103]
	v_mfma_f32_16x16x32_bf16 v[96:99], v[182:185], v[198:201], v[96:99]
	v_mfma_f32_16x16x32_bf16 v[84:87], v[174:177], v[208:211], v[84:87]
	v_mfma_f32_16x16x32_bf16 v[80:83], v[182:185], v[208:211], v[80:83]
	v_mfma_f32_16x16x32_bf16 v[68:71], v[174:177], v[216:219], v[68:71]
	v_mfma_f32_16x16x32_bf16 v[64:67], v[182:185], v[216:219], v[64:67]
	s_setprio 0
	s_barrier
	s_add_i32 s40, s73, s3
	s_mov_b32 m0, s40
	ds_read_b128 v[186:189], v155 offset:49152
	ds_read_b128 v[190:193], v155 offset:50176
	ds_read_b128 v[194:197], v155 offset:51200
	ds_read_b128 v[198:201], v155 offset:52224
	ds_read_b128 v[204:207], v155 offset:53248
	ds_read_b128 v[208:211], v155 offset:54272
	ds_read_b128 v[212:215], v155 offset:55296
	ds_read_b128 v[216:219], v155 offset:56320
	global_load_lds_dwordx4 v130, s[98:99]
	s_add_i32 m0, s40, 0x2000
	s_add_u32 s38, s38, 0x40080
	s_addc_u32 s39, s39, 0
	s_add_i32 s40, s79, s3
	global_load_lds_dwordx4 v134, s[98:99]
	s_mov_b32 m0, s40
	s_nop 0
	global_load_lds_dwordx4 v130, s[38:39]
	s_add_i32 m0, s40, 0x2000
	s_nop 0
	global_load_lds_dwordx4 v134, s[38:39]
	s_mov_b32 m0, s66
	s_nop 0
	global_load_lds_dwordx4 v128, s[100:101]
	s_mov_b32 m0, s67
	s_nop 0
	global_load_lds_dwordx4 v132, s[100:101]
	s_waitcnt vmcnt(8)
	s_waitcnt lgkmcnt(0)
	s_barrier
	s_setprio 1
	s_waitcnt lgkmcnt(0)
	v_mfma_f32_16x16x32_bf16 v[60:63], v[144:147], v[186:189], v[60:63]
	v_mfma_f32_16x16x32_bf16 v[56:59], v[162:165], v[186:189], v[56:59]
	v_mfma_f32_16x16x32_bf16 v[44:47], v[144:147], v[194:197], v[44:47]
	v_mfma_f32_16x16x32_bf16 v[40:43], v[162:165], v[194:197], v[40:43]
	v_mfma_f32_16x16x32_bf16 v[28:31], v[144:147], v[204:207], v[28:31]
	v_mfma_f32_16x16x32_bf16 v[24:27], v[162:165], v[204:207], v[24:27]
	v_mfma_f32_16x16x32_bf16 v[12:15], v[144:147], v[212:215], v[12:15]
	v_mfma_f32_16x16x32_bf16 v[8:11], v[162:165], v[212:215], v[8:11]
	v_mfma_f32_16x16x32_bf16 v[60:63], v[158:161], v[190:193], v[60:63]
	v_mfma_f32_16x16x32_bf16 v[56:59], v[166:169], v[190:193], v[56:59]
	v_mfma_f32_16x16x32_bf16 v[44:47], v[158:161], v[198:201], v[44:47]
	v_mfma_f32_16x16x32_bf16 v[40:43], v[166:169], v[198:201], v[40:43]
	v_mfma_f32_16x16x32_bf16 v[28:31], v[158:161], v[208:211], v[28:31]
	v_mfma_f32_16x16x32_bf16 v[24:27], v[166:169], v[208:211], v[24:27]
	v_mfma_f32_16x16x32_bf16 v[12:15], v[158:161], v[216:219], v[12:15]
	v_mfma_f32_16x16x32_bf16 v[8:11], v[166:169], v[216:219], v[8:11]
	s_setprio 0
	s_setprio 1
	v_mfma_f32_16x16x32_bf16 v[52:55], v[170:173], v[186:189], v[52:55]
	v_mfma_f32_16x16x32_bf16 v[48:51], v[178:181], v[186:189], v[48:51]
	v_mfma_f32_16x16x32_bf16 v[36:39], v[170:173], v[194:197], v[36:39]
	v_mfma_f32_16x16x32_bf16 v[32:35], v[178:181], v[194:197], v[32:35]
	v_mfma_f32_16x16x32_bf16 v[20:23], v[170:173], v[204:207], v[20:23]
	v_mfma_f32_16x16x32_bf16 v[16:19], v[178:181], v[204:207], v[16:19]
	v_mfma_f32_16x16x32_bf16 v[4:7], v[170:173], v[212:215], v[4:7]
	v_mfma_f32_16x16x32_bf16 v[0:3], v[178:181], v[212:215], v[0:3]
	v_mfma_f32_16x16x32_bf16 v[52:55], v[174:177], v[190:193], v[52:55]
	v_mfma_f32_16x16x32_bf16 v[48:51], v[182:185], v[190:193], v[48:51]
	v_mfma_f32_16x16x32_bf16 v[36:39], v[174:177], v[198:201], v[36:39]
	v_mfma_f32_16x16x32_bf16 v[32:35], v[182:185], v[198:201], v[32:35]
	v_mfma_f32_16x16x32_bf16 v[20:23], v[174:177], v[208:211], v[20:23]
	v_mfma_f32_16x16x32_bf16 v[16:19], v[182:185], v[208:211], v[16:19]
	v_mfma_f32_16x16x32_bf16 v[4:7], v[174:177], v[216:219], v[4:7]
	v_mfma_f32_16x16x32_bf16 v[0:3], v[182:185], v[216:219], v[0:3]
	s_setprio 0
	s_barrier
	s_add_i32 s72, s72, 2
	s_add_u32 s36, s36, 0x100
	s_addc_u32 s37, s37, 0
	s_add_u32 s29, s29, 0x100
	s_addc_u32 s71, s71, 0
	s_cmp_gt_u32 s72, 13
	s_cbranch_scc0 .LBB0_821
	s_and_b64 vcc, exec, s[22:23]
	s_cbranch_vccz .LBB0_824
	s_barrier

; #define PG8_STAGE(bufoff, gbase, voff) do { _Pragma("unroll") for (int _i = 0; _i < 2; ++_i) \
;         __builtin_amdgcn_global_load_lds((const unsigned*)((const char*)(gbase) + (voff)[_i]), (LAS unsigned*)(lds + (bufoff) + ldsw + _i * 8192), 16, 0, 0); } while (0)
; #define PG8_LDA(dst, b, h) do { _Pragma("unroll") for (int m = 0; m < 4; ++m) _Pragma("unroll") for (int k = 0; k < 2; ++k) dst[m][k] = *(const LAS bf16x8*)(lds + PG8_SA(b, h) + aoff + m * 2048 + k * 1024); } while (0)
; #define PG8_LDB(dst, b, h) do { _Pragma("unroll") for (int n = 0; n < 2; ++n) _Pragma("unroll") for (int k = 0; k < 2; ++k) dst[n][k] = *(const LAS bf16x8*)(lds + PG8_SB(b, h) + boff + n * 2048 + k * 1024); } while (0)
; #define PG8_MMA(ai, bj, At, Bt) do { __builtin_amdgcn_s_setprio(1); _Pragma("unroll") for (int m = 0; m < 4; ++m) _Pragma("unroll") for (int n = 0; n < 2; ++n) _Pragma("unroll") for (int k = 0; k < 2; ++k) \
;         acc[ai][bj][m][n] = __builtin_amdgcn_mfma_f32_16x16x32_bf16(Bt[n][k], At[m][k], acc[ai][bj][m][n], 0, 0, 0); __builtin_amdgcn_s_setprio(0); } while (0)
; #define PG8_WAIT_V(n) asm volatile("s_waitcnt vmcnt(" #n ")" ::: "memory")
; #define PG8_WAIT_L(n) asm volatile("s_waitcnt lgkmcnt(" #n ")" ::: "memory")
; #define PG8_BAR __builtin_amdgcn_s_barrier()
; #define PG8_SCHED __builtin_amdgcn_sched_barrier(0)
; template <class Epi, class Sched, bool ALIGN_EPI>
; __device__ __forceinline__ void gemm_phase(LAS unsigned char* lds, const GemmDesc g, const Sched& S, const Epi& E) {
;     ...
;             const bool last = (t == nt - 2);
;             const char* a1 = cA + (size_t)(t + 1) * kstep;
;             const char* a2 = last ? nA : cA + (size_t)(t + 2) * kstep; const char* b2 = last ? nB : cB + (size_t)(t + 2) * kstep;
;             const char* a3 = a2 + kstep; const char* b3 = b2 + kstep;
;             PG8_LDB(B0, 0, 0); PG8_LDB(B1, 0, 1); PG8_SCHED; PG8_LDA(At, 0, 0); PG8_STAGE(PG8_SA(1, 1), a1 + hstepA, voffA);
;             PG8_WAIT_V(8); PG8_WAIT_L(0); PG8_BAR; PG8_MMA(0, 0, At, B0); PG8_MMA(0, 1, At, B1); PG8_BAR; PG8_SCHED;
;             PG8_LDA(At, 0, 1); PG8_STAGE(PG8_SB(0, 0), b2, voffB); PG8_STAGE(PG8_SB(0, 1), b2 + hstepB, voffB); PG8_STAGE(PG8_SA(0, 0), a2, voffA);
;             PG8_WAIT_V(8); PG8_WAIT_L(0); PG8_BAR; PG8_MMA(1, 0, At, B0); PG8_MMA(1, 1, At, B1); PG8_BAR; PG8_SCHED;
.LBB0_942:
	ds_read_b128 v[128:131], v181
	ds_read_b128 v[132:135], v181 offset:1024
	ds_read_b128 v[136:139], v181 offset:2048
	ds_read_b128 v[140:143], v181 offset:3072
	ds_read_b128 v[144:147], v182
	ds_read_b128 v[148:151], v182 offset:1024
	ds_read_b128 v[152:155], v182 offset:2048
	ds_read_b128 v[156:159], v182 offset:3072
	s_add_u32 s40, s64, 0xfffc0080
	s_addc_u32 s41, s65, -1
	s_cmp_eq_u32 s82, 12
	s_cselect_b32 s67, s21, s41
	s_cselect_b32 s66, s29, s40
	s_cselect_b32 s41, s27, s81
	s_cselect_b32 s40, s79, s80
	s_add_i32 m0, s5, 0xc000
	ds_read_b128 v[174:177], v183
	ds_read_b128 v[186:189], v183 offset:1024
	ds_read_b128 v[190:193], v183 offset:2048
	ds_read_b128 v[194:197], v183 offset:3072
	ds_read_b128 v[198:201], v183 offset:4096
	ds_read_b128 v[204:207], v183 offset:5120
	ds_read_b128 v[208:211], v183 offset:6144
	ds_read_b128 v[212:215], v183 offset:7168
	global_load_lds_dwordx4 v168, s[64:65]
	s_add_i32 m0, s5, 0xe000
	s_nop 0
	global_load_lds_dwordx4 v170, s[64:65]
	s_waitcnt vmcnt(8)
	s_waitcnt lgkmcnt(0)
	s_barrier
	s_setprio 1
	s_waitcnt lgkmcnt(0)
	v_mfma_f32_16x16x32_bf16 v[124:127], v[128:131], v[174:177], v[124:127]
	v_mfma_f32_16x16x32_bf16 v[120:123], v[136:139], v[174:177], v[120:123]
	v_mfma_f32_16x16x32_bf16 v[116:119], v[128:131], v[190:193], v[116:119]
	v_mfma_f32_16x16x32_bf16 v[112:115], v[136:139], v[190:193], v[112:115]
	v_mfma_f32_16x16x32_bf16 v[92:95], v[128:131], v[198:201], v[92:95]
	v_mfma_f32_16x16x32_bf16 v[88:91], v[136:139], v[198:201], v[88:91]
	v_mfma_f32_16x16x32_bf16 v[76:79], v[128:131], v[208:211], v[76:79]
	v_mfma_f32_16x16x32_bf16 v[72:75], v[136:139], v[208:211], v[72:75]
	v_mfma_f32_16x16x32_bf16 v[124:127], v[132:135], v[186:189], v[124:127]
	v_mfma_f32_16x16x32_bf16 v[120:123], v[140:143], v[186:189], v[120:123]
	v_mfma_f32_16x16x32_bf16 v[116:119], v[132:135], v[194:197], v[116:119]
	v_mfma_f32_16x16x32_bf16 v[112:115], v[140:143], v[194:197], v[112:115]
	v_mfma_f32_16x16x32_bf16 v[92:95], v[132:135], v[204:207], v[92:95]
	v_mfma_f32_16x16x32_bf16 v[88:91], v[140:143], v[204:207], v[88:91]
	v_mfma_f32_16x16x32_bf16 v[76:79], v[132:135], v[212:215], v[76:79]
	v_mfma_f32_16x16x32_bf16 v[72:75], v[140:143], v[212:215], v[72:75]
	s_setprio 0
	s_setprio 1
	v_mfma_f32_16x16x32_bf16 v[108:111], v[144:147], v[174:177], v[108:111]
	v_mfma_f32_16x16x32_bf16 v[104:107], v[152:155], v[174:177], v[104:107]
	v_mfma_f32_16x16x32_bf16 v[100:103], v[144:147], v[190:193], v[100:103]
	v_mfma_f32_16x16x32_bf16 v[96:99], v[152:155], v[190:193], v[96:99]
	v_mfma_f32_16x16x32_bf16 v[84:87], v[144:147], v[198:201], v[84:87]
	v_mfma_f32_16x16x32_bf16 v[80:83], v[152:155], v[198:201], v[80:83]
	v_mfma_f32_16x16x32_bf16 v[68:71], v[144:147], v[208:211], v[68:71]
	v_mfma_f32_16x16x32_bf16 v[64:67], v[152:155], v[208:211], v[64:67]
	v_mfma_f32_16x16x32_bf16 v[108:111], v[148:151], v[186:189], v[108:111]
	v_mfma_f32_16x16x32_bf16 v[104:107], v[156:159], v[186:189], v[104:107]
	v_mfma_f32_16x16x32_bf16 v[100:103], v[148:151], v[194:197], v[100:103]
	v_mfma_f32_16x16x32_bf16 v[96:99], v[156:159], v[194:197], v[96:99]
	v_mfma_f32_16x16x32_bf16 v[84:87], v[148:151], v[204:207], v[84:87]
	v_mfma_f32_16x16x32_bf16 v[80:83], v[156:159], v[204:207], v[80:83]
	v_mfma_f32_16x16x32_bf16 v[68:71], v[148:151], v[212:215], v[68:71]
	v_mfma_f32_16x16x32_bf16 v[64:67], v[156:159], v[212:215], v[64:67]
	s_setprio 0
	s_barrier
	s_add_i32 s83, s71, s4
	s_add_u32 s98, s40, s18
	s_addc_u32 s99, s41, s19
	s_mov_b32 m0, s83
	ds_read_b128 v[174:177], v183 offset:16384
	ds_read_b128 v[186:189], v183 offset:17408
	ds_read_b128 v[190:193], v183 offset:18432
	ds_read_b128 v[194:197], v183 offset:19456
	ds_read_b128 v[198:201], v183 offset:20480
	ds_read_b128 v[204:207], v183 offset:21504
	ds_read_b128 v[208:211], v183 offset:22528
	ds_read_b128 v[212:215], v183 offset:23552
	global_load_lds_dwordx4 v162, s[40:41]
	s_add_i32 m0, s83, 0x2000
	s_add_u32 s88, s40, 0x40000
	s_addc_u32 s89, s41, 0
	s_add_i32 s83, s72, s4
	global_load_lds_dwordx4 v166, s[40:41]
	s_mov_b32 m0, s83
	s_nop 0
	global_load_lds_dwordx4 v162, s[88:89]
	s_add_i32 m0, s83, 0x2000
	s_nop 0
	global_load_lds_dwordx4 v166, s[88:89]
	s_add_u32 s100, s66, s18
	s_addc_u32 s101, s67, s19
	s_mov_b32 m0, s5
	s_nop 0
	global_load_lds_dwordx4 v160, s[66:67]
	s_mov_b32 m0, s7
	s_nop 0
	global_load_lds_dwordx4 v164, s[66:67]
	s_waitcnt vmcnt(8)
	s_waitcnt lgkmcnt(0)
	s_barrier
	s_setprio 1
	s_waitcnt lgkmcnt(0)
	v_mfma_f32_16x16x32_bf16 v[60:63], v[128:131], v[174:177], v[60:63]
	v_mfma_f32_16x16x32_bf16 v[56:59], v[136:139], v[174:177], v[56:59]
	v_mfma_f32_16x16x32_bf16 v[44:47], v[128:131], v[190:193], v[44:47]
	v_mfma_f32_16x16x32_bf16 v[40:43], v[136:139], v[190:193], v[40:43]
	v_mfma_f32_16x16x32_bf16 v[28:31], v[128:131], v[198:201], v[28:31]
	v_mfma_f32_16x16x32_bf16 v[24:27], v[136:139], v[198:201], v[24:27]
	v_mfma_f32_16x16x32_bf16 v[12:15], v[128:131], v[208:211], v[12:15]
	v_mfma_f32_16x16x32_bf16 v[8:11], v[136:139], v[208:211], v[8:11]
	v_mfma_f32_16x16x32_bf16 v[60:63], v[132:135], v[186:189], v[60:63]
	v_mfma_f32_16x16x32_bf16 v[56:59], v[140:143], v[186:189], v[56:59]
	v_mfma_f32_16x16x32_bf16 v[44:47], v[132:135], v[194:197], v[44:47]
	v_mfma_f32_16x16x32_bf16 v[40:43], v[140:143], v[194:197], v[40:43]
	v_mfma_f32_16x16x32_bf16 v[28:31], v[132:135], v[204:207], v[28:31]
	v_mfma_f32_16x16x32_bf16 v[24:27], v[140:143], v[204:207], v[24:27]
	v_mfma_f32_16x16x32_bf16 v[12:15], v[132:135], v[212:215], v[12:15]
	v_mfma_f32_16x16x32_bf16 v[8:11], v[140:143], v[212:215], v[8:11]
	s_setprio 0
	s_setprio 1
	v_mfma_f32_16x16x32_bf16 v[52:55], v[144:147], v[174:177], v[52:55]
	v_mfma_f32_16x16x32_bf16 v[48:51], v[152:155], v[174:177], v[48:51]
	v_mfma_f32_16x16x32_bf16 v[36:39], v[144:147], v[190:193], v[36:39]
	v_mfma_f32_16x16x32_bf16 v[32:35], v[152:155], v[190:193], v[32:35]
	v_mfma_f32_16x16x32_bf16 v[20:23], v[144:147], v[198:201], v[20:23]
	v_mfma_f32_16x16x32_bf16 v[16:19], v[152:155], v[198:201], v[16:19]
	v_mfma_f32_16x16x32_bf16 v[4:7], v[144:147], v[208:211], v[4:7]
	v_mfma_f32_16x16x32_bf16 v[0:3], v[152:155], v[208:211], v[0:3]
	v_mfma_f32_16x16x32_bf16 v[52:55], v[148:151], v[186:189], v[52:55]
	v_mfma_f32_16x16x32_bf16 v[48:51], v[156:159], v[186:189], v[48:51]
	v_mfma_f32_16x16x32_bf16 v[36:39], v[148:151], v[194:197], v[36:39]
	v_mfma_f32_16x16x32_bf16 v[32:35], v[156:159], v[194:197], v[32:35]
	v_mfma_f32_16x16x32_bf16 v[20:23], v[148:151], v[204:207], v[20:23]
	v_mfma_f32_16x16x32_bf16 v[16:19], v[156:159], v[204:207], v[16:19]
	v_mfma_f32_16x16x32_bf16 v[4:7], v[148:151], v[212:215], v[4:7]
	v_mfma_f32_16x16x32_bf16 v[0:3], v[156:159], v[212:215], v[0:3]
	s_setprio 0
	s_barrier
; #define PG8_STAGE(bufoff, gbase, voff) do { _Pragma("unroll") for (int _i = 0; _i < 2; ++_i) \
;         __builtin_amdgcn_global_load_lds((const unsigned*)((const char*)(gbase) + (voff)[_i]), (LAS unsigned*)(lds + (bufoff) + ldsw + _i * 8192), 16, 0, 0); } while (0)
; #define PG8_LDA(dst, b, h) do { _Pragma("unroll") for (int m = 0; m < 4; ++m) _Pragma("unroll") for (int k = 0; k < 2; ++k) dst[m][k] = *(const LAS bf16x8*)(lds + PG8_SA(b, h) + aoff + m * 2048 + k * 1024); } while (0)
; #define PG8_LDB(dst, b, h) do { _Pragma("unroll") for (int n = 0; n < 2; ++n) _Pragma("unroll") for (int k = 0; k < 2; ++k) dst[n][k] = *(const LAS bf16x8*)(lds + PG8_SB(b, h) + boff + n * 2048 + k * 1024); } while (0)
; #define PG8_MMA(ai, bj, At, Bt) do { __builtin_amdgcn_s_setprio(1); _Pragma("unroll") for (int m = 0; m < 4; ++m) _Pragma("unroll") for (int n = 0; n < 2; ++n) _Pragma("unroll") for (int k = 0; k < 2; ++k) \
;         acc[ai][bj][m][n] = __builtin_amdgcn_mfma_f32_16x16x32_bf16(Bt[n][k], At[m][k], acc[ai][bj][m][n], 0, 0, 0); __builtin_amdgcn_s_setprio(0); } while (0)
; #define PG8_WAIT_V(n) asm volatile("s_waitcnt vmcnt(" #n ")" ::: "memory")
; #define PG8_WAIT_L(n) asm volatile("s_waitcnt lgkmcnt(" #n ")" ::: "memory")
; #define PG8_BAR __builtin_amdgcn_s_barrier()
; #define PG8_SCHED __builtin_amdgcn_sched_barrier(0)
; template <class Epi, class Sched, bool ALIGN_EPI>
; __device__ __forceinline__ void gemm_phase(LAS unsigned char* lds, const GemmDesc g, const Sched& S, const Epi& E) {
;     ...
;             PG8_LDB(B0, 1, 0); PG8_LDB(B1, 1, 1); PG8_SCHED; PG8_LDA(At, 1, 0); PG8_STAGE(PG8_SA(0, 1), a2 + hstepA, voffA);
;             PG8_WAIT_V(8); PG8_WAIT_L(0); PG8_BAR; PG8_MMA(0, 0, At, B0); PG8_MMA(0, 1, At, B1); PG8_BAR; PG8_SCHED;
;             PG8_LDA(At, 1, 1); PG8_STAGE(PG8_SB(1, 0), b3, voffB); PG8_STAGE(PG8_SB(1, 1), b3 + hstepB, voffB); PG8_STAGE(PG8_SA(1, 0), a3, voffA);
;             PG8_WAIT_V(8); PG8_WAIT_L(0); PG8_BAR; PG8_MMA(1, 0, At, B0); PG8_MMA(1, 1, At, B1); PG8_BAR; PG8_SCHED;
;         }
	s_add_i32 s83, 0, 0x18000
	s_add_i32 s84, 0, 0x1c000
	v_add_u32_e32 v140, s83, v180
	v_add_u32_e32 v156, s84, v180
	ds_read_b128 v[128:131], v140
	ds_read_b128 v[132:135], v140 offset:1024
	ds_read_b128 v[136:139], v140 offset:2048
	ds_read_b128 v[140:143], v140 offset:3072
	ds_read_b128 v[144:147], v156
	ds_read_b128 v[148:151], v156 offset:1024
	ds_read_b128 v[152:155], v156 offset:2048
	ds_read_b128 v[156:159], v156 offset:3072
	s_add_u32 s66, s66, 0x40000
	s_addc_u32 s67, s67, 0
	s_mov_b32 m0, s25
	ds_read_b128 v[174:177], v183 offset:32768
	ds_read_b128 v[186:189], v183 offset:33792
	ds_read_b128 v[190:193], v183 offset:34816
	ds_read_b128 v[194:197], v183 offset:35840
	ds_read_b128 v[198:201], v183 offset:36864
	ds_read_b128 v[204:207], v183 offset:37888
	ds_read_b128 v[208:211], v183 offset:38912
	ds_read_b128 v[212:215], v183 offset:39936
	global_load_lds_dwordx4 v160, s[66:67]
	s_mov_b32 m0, s39
	s_nop 0
	global_load_lds_dwordx4 v164, s[66:67]
	s_waitcnt vmcnt(8)
	s_waitcnt lgkmcnt(0)
	s_barrier
	s_setprio 1
	s_waitcnt lgkmcnt(0)
	v_mfma_f32_16x16x32_bf16 v[124:127], v[128:131], v[174:177], v[124:127]
	v_mfma_f32_16x16x32_bf16 v[120:123], v[136:139], v[174:177], v[120:123]
	v_mfma_f32_16x16x32_bf16 v[116:119], v[128:131], v[190:193], v[116:119]
	v_mfma_f32_16x16x32_bf16 v[112:115], v[136:139], v[190:193], v[112:115]
	v_mfma_f32_16x16x32_bf16 v[92:95], v[128:131], v[198:201], v[92:95]
	v_mfma_f32_16x16x32_bf16 v[88:91], v[136:139], v[198:201], v[88:91]
	v_mfma_f32_16x16x32_bf16 v[76:79], v[128:131], v[208:211], v[76:79]
	v_mfma_f32_16x16x32_bf16 v[72:75], v[136:139], v[208:211], v[72:75]
	v_mfma_f32_16x16x32_bf16 v[124:127], v[132:135], v[186:189], v[124:127]
	v_mfma_f32_16x16x32_bf16 v[120:123], v[140:143], v[186:189], v[120:123]
	v_mfma_f32_16x16x32_bf16 v[116:119], v[132:135], v[194:197], v[116:119]
	v_mfma_f32_16x16x32_bf16 v[112:115], v[140:143], v[194:197], v[112:115]
	v_mfma_f32_16x16x32_bf16 v[92:95], v[132:135], v[204:207], v[92:95]
	v_mfma_f32_16x16x32_bf16 v[88:91], v[140:143], v[204:207], v[88:91]
	v_mfma_f32_16x16x32_bf16 v[76:79], v[132:135], v[212:215], v[76:79]
	v_mfma_f32_16x16x32_bf16 v[72:75], v[140:143], v[212:215], v[72:75]
	s_setprio 0
	s_setprio 1
	v_mfma_f32_16x16x32_bf16 v[108:111], v[144:147], v[174:177], v[108:111]
	v_mfma_f32_16x16x32_bf16 v[104:107], v[152:155], v[174:177], v[104:107]
	v_mfma_f32_16x16x32_bf16 v[100:103], v[144:147], v[190:193], v[100:103]
	v_mfma_f32_16x16x32_bf16 v[96:99], v[152:155], v[190:193], v[96:99]
	v_mfma_f32_16x16x32_bf16 v[84:87], v[144:147], v[198:201], v[84:87]
	v_mfma_f32_16x16x32_bf16 v[80:83], v[152:155], v[198:201], v[80:83]
	v_mfma_f32_16x16x32_bf16 v[68:71], v[144:147], v[208:211], v[68:71]
	v_mfma_f32_16x16x32_bf16 v[64:67], v[152:155], v[208:211], v[64:67]
	v_mfma_f32_16x16x32_bf16 v[108:111], v[148:151], v[186:189], v[108:111]
	v_mfma_f32_16x16x32_bf16 v[104:107], v[156:159], v[186:189], v[104:107]
	v_mfma_f32_16x16x32_bf16 v[100:103], v[148:151], v[194:197], v[100:103]
	v_mfma_f32_16x16x32_bf16 v[96:99], v[156:159], v[194:197], v[96:99]
	v_mfma_f32_16x16x32_bf16 v[84:87], v[148:151], v[204:207], v[84:87]
	v_mfma_f32_16x16x32_bf16 v[80:83], v[156:159], v[204:207], v[80:83]
	v_mfma_f32_16x16x32_bf16 v[68:71], v[148:151], v[212:215], v[68:71]
	v_mfma_f32_16x16x32_bf16 v[64:67], v[156:159], v[212:215], v[64:67]
	s_setprio 0
	s_barrier
	s_add_i32 s66, s83, s4
	s_mov_b32 m0, s66
	ds_read_b128 v[174:177], v183 offset:49152
	ds_read_b128 v[186:189], v183 offset:50176
	ds_read_b128 v[190:193], v183 offset:51200
	ds_read_b128 v[194:197], v183 offset:52224
	ds_read_b128 v[198:201], v183 offset:53248
	ds_read_b128 v[204:207], v183 offset:54272
	ds_read_b128 v[208:211], v183 offset:55296
	ds_read_b128 v[212:215], v183 offset:56320
	global_load_lds_dwordx4 v162, s[98:99]
	s_add_i32 m0, s66, 0x2000
	s_add_u32 s40, s40, 0x40080
	s_addc_u32 s41, s41, 0
	s_add_i32 s66, s84, s4
	global_load_lds_dwordx4 v166, s[98:99]
	s_mov_b32 m0, s66
	s_nop 0
	global_load_lds_dwordx4 v162, s[40:41]
	s_add_i32 m0, s66, 0x2000
	s_nop 0
	global_load_lds_dwordx4 v166, s[40:41]
	s_mov_b32 m0, s68
	s_nop 0
	global_load_lds_dwordx4 v160, s[100:101]
	s_mov_b32 m0, s69
	s_nop 0
	global_load_lds_dwordx4 v164, s[100:101]
	s_waitcnt vmcnt(8)
	s_waitcnt lgkmcnt(0)
	s_barrier
	s_setprio 1
	s_waitcnt lgkmcnt(0)
	v_mfma_f32_16x16x32_bf16 v[60:63], v[128:131], v[174:177], v[60:63]
	v_mfma_f32_16x16x32_bf16 v[56:59], v[136:139], v[174:177], v[56:59]
	v_mfma_f32_16x16x32_bf16 v[44:47], v[128:131], v[190:193], v[44:47]
	v_mfma_f32_16x16x32_bf16 v[40:43], v[136:139], v[190:193], v[40:43]
	v_mfma_f32_16x16x32_bf16 v[28:31], v[128:131], v[198:201], v[28:31]
	v_mfma_f32_16x16x32_bf16 v[24:27], v[136:139], v[198:201], v[24:27]
	v_mfma_f32_16x16x32_bf16 v[12:15], v[128:131], v[208:211], v[12:15]
	v_mfma_f32_16x16x32_bf16 v[8:11], v[136:139], v[208:211], v[8:11]
	v_mfma_f32_16x16x32_bf16 v[60:63], v[132:135], v[186:189], v[60:63]
	v_mfma_f32_16x16x32_bf16 v[56:59], v[140:143], v[186:189], v[56:59]
	v_mfma_f32_16x16x32_bf16 v[44:47], v[132:135], v[194:197], v[44:47]
	v_mfma_f32_16x16x32_bf16 v[40:43], v[140:143], v[194:197], v[40:43]
	v_mfma_f32_16x16x32_bf16 v[28:31], v[132:135], v[204:207], v[28:31]
	v_mfma_f32_16x16x32_bf16 v[24:27], v[140:143], v[204:207], v[24:27]
	v_mfma_f32_16x16x32_bf16 v[12:15], v[132:135], v[212:215], v[12:15]
	v_mfma_f32_16x16x32_bf16 v[8:11], v[140:143], v[212:215], v[8:11]
	s_setprio 0
	s_setprio 1
	v_mfma_f32_16x16x32_bf16 v[52:55], v[144:147], v[174:177], v[52:55]
	v_mfma_f32_16x16x32_bf16 v[48:51], v[152:155], v[174:177], v[48:51]
	v_mfma_f32_16x16x32_bf16 v[36:39], v[144:147], v[190:193], v[36:39]
	v_mfma_f32_16x16x32_bf16 v[32:35], v[152:155], v[190:193], v[32:35]
	v_mfma_f32_16x16x32_bf16 v[20:23], v[144:147], v[198:201], v[20:23]
	v_mfma_f32_16x16x32_bf16 v[16:19], v[152:155], v[198:201], v[16:19]
	v_mfma_f32_16x16x32_bf16 v[4:7], v[144:147], v[208:211], v[4:7]
	v_mfma_f32_16x16x32_bf16 v[0:3], v[152:155], v[208:211], v[0:3]
	v_mfma_f32_16x16x32_bf16 v[52:55], v[148:151], v[186:189], v[52:55]
	v_mfma_f32_16x16x32_bf16 v[48:51], v[156:159], v[186:189], v[48:51]
	v_mfma_f32_16x16x32_bf16 v[36:39], v[148:151], v[194:197], v[36:39]
	v_mfma_f32_16x16x32_bf16 v[32:35], v[156:159], v[194:197], v[32:35]
	v_mfma_f32_16x16x32_bf16 v[20:23], v[148:151], v[204:207], v[20:23]
	v_mfma_f32_16x16x32_bf16 v[16:19], v[156:159], v[204:207], v[16:19]
	v_mfma_f32_16x16x32_bf16 v[4:7], v[148:151], v[212:215], v[4:7]
	v_mfma_f32_16x16x32_bf16 v[0:3], v[156:159], v[212:215], v[0:3]
	s_setprio 0
	s_barrier
	s_add_i32 s82, s82, 2
	s_add_u32 s64, s64, 0x100
	s_addc_u32 s65, s65, 0
	s_add_u32 s80, s80, 0x100
	s_addc_u32 s81, s81, 0
	s_cmp_gt_u32 s82, 13
	s_cbranch_scc0 .LBB0_942
	s_and_b64 vcc, exec, s[22:23]
	s_cbranch_vccz .LBB0_945
	s_barrier

; #define PG8_STAGE(bufoff, gbase, voff) do { _Pragma("unroll") for (int _i = 0; _i < 2; ++_i) \
;         __builtin_amdgcn_global_load_lds((const unsigned*)((const char*)(gbase) + (voff)[_i]), (LAS unsigned*)(lds + (bufoff) + ldsw + _i * 8192), 16, 0, 0); } while (0)
; #define PG8_LDA(dst, b, h) do { _Pragma("unroll") for (int m = 0; m < 4; ++m) _Pragma("unroll") for (int k = 0; k < 2; ++k) dst[m][k] = *(const LAS bf16x8*)(lds + PG8_SA(b, h) + aoff + m * 2048 + k * 1024); } while (0)
; #define PG8_LDB(dst, b, h) do { _Pragma("unroll") for (int n = 0; n < 2; ++n) _Pragma("unroll") for (int k = 0; k < 2; ++k) dst[n][k] = *(const LAS bf16x8*)(lds + PG8_SB(b, h) + boff + n * 2048 + k * 1024); } while (0)
; #define PG8_MMA(ai, bj, At, Bt) do { __builtin_amdgcn_s_setprio(1); _Pragma("unroll") for (int m = 0; m < 4; ++m) _Pragma("unroll") for (int n = 0; n < 2; ++n) _Pragma("unroll") for (int k = 0; k < 2; ++k) \
;         acc[ai][bj][m][n] = __builtin_amdgcn_mfma_f32_16x16x32_bf16(Bt[n][k], At[m][k], acc[ai][bj][m][n], 0, 0, 0); __builtin_amdgcn_s_setprio(0); } while (0)
; #define PG8_WAIT_V(n) asm volatile("s_waitcnt vmcnt(" #n ")" ::: "memory")
; #define PG8_WAIT_L(n) asm volatile("s_waitcnt lgkmcnt(" #n ")" ::: "memory")
; #define PG8_BAR __builtin_amdgcn_s_barrier()
; #define PG8_SCHED __builtin_amdgcn_sched_barrier(0)
; template <class Epi, class Sched, bool ALIGN_EPI>
; __device__ __forceinline__ void gemm_phase(LAS unsigned char* lds, const GemmDesc g, const Sched& S, const Epi& E) {
;     ...
;             const bool last = (t == nt - 2);
;             const char* a1 = cA + (size_t)(t + 1) * kstep;
;             const char* a2 = last ? nA : cA + (size_t)(t + 2) * kstep; const char* b2 = last ? nB : cB + (size_t)(t + 2) * kstep;
;             const char* a3 = a2 + kstep; const char* b3 = b2 + kstep;
;             PG8_LDB(B0, 0, 0); PG8_LDB(B1, 0, 1); PG8_SCHED; PG8_LDA(At, 0, 0); PG8_STAGE(PG8_SA(1, 1), a1 + hstepA, voffA);
;             PG8_WAIT_V(8); PG8_WAIT_L(0); PG8_BAR; PG8_MMA(0, 0, At, B0); PG8_MMA(0, 1, At, B1); PG8_BAR; PG8_SCHED;
;             PG8_LDA(At, 0, 1); PG8_STAGE(PG8_SB(0, 0), b2, voffB); PG8_STAGE(PG8_SB(0, 1), b2 + hstepB, voffB); PG8_STAGE(PG8_SA(0, 0), a2, voffA);
;             PG8_WAIT_V(8); PG8_WAIT_L(0); PG8_BAR; PG8_MMA(1, 0, At, B0); PG8_MMA(1, 1, At, B1); PG8_BAR; PG8_SCHED;
.LBB0_1257:
	ds_read_b128 v[64:67], v188
	ds_read_b128 v[68:71], v188 offset:1024
	ds_read_b128 v[72:75], v188 offset:2048
	ds_read_b128 v[76:79], v188 offset:3072
	ds_read_b128 v[80:83], v189
	ds_read_b128 v[84:87], v189 offset:1024
	ds_read_b128 v[88:91], v189 offset:2048
	ds_read_b128 v[92:95], v189 offset:3072
	s_add_u32 s22, s10, 0xfffc0080
	s_addc_u32 s35, s11, -1
	s_cmp_eq_u32 s7, 12
	s_cselect_b32 s65, s1, s35
	s_cselect_b32 s64, s4, s22
	s_cselect_b32 s41, s47, s6
	s_cselect_b32 s40, s46, s5
	s_add_i32 m0, s21, 0xc000
	ds_read_b128 v[176:179], v190
	ds_read_b128 v[180:183], v190 offset:1024
	ds_read_b128 v[192:195], v190 offset:2048
	ds_read_b128 v[196:199], v190 offset:3072
	ds_read_b128 v[204:207], v190 offset:4096
	ds_read_b128 v[208:211], v190 offset:5120
	ds_read_b128 v[212:215], v190 offset:6144
	ds_read_b128 v[216:219], v190 offset:7168
	global_load_lds_dwordx4 v168, s[10:11]
	s_add_i32 m0, s21, 0xe000
	s_nop 0
	global_load_lds_dwordx4 v170, s[10:11]
	s_waitcnt vmcnt(8)
	s_waitcnt lgkmcnt(0)
	s_barrier
	s_setprio 1
	s_waitcnt lgkmcnt(0)
	v_mfma_f32_16x16x32_bf16 v[156:159], v[64:67], v[176:179], v[156:159]
	v_mfma_f32_16x16x32_bf16 v[152:155], v[72:75], v[176:179], v[152:155]
	v_mfma_f32_16x16x32_bf16 v[140:143], v[64:67], v[192:195], v[140:143]
	v_mfma_f32_16x16x32_bf16 v[136:139], v[72:75], v[192:195], v[136:139]
	v_mfma_f32_16x16x32_bf16 v[124:127], v[64:67], v[204:207], v[124:127]
	v_mfma_f32_16x16x32_bf16 v[120:123], v[72:75], v[204:207], v[120:123]
	v_mfma_f32_16x16x32_bf16 v[108:111], v[64:67], v[212:215], v[108:111]
	v_mfma_f32_16x16x32_bf16 v[104:107], v[72:75], v[212:215], v[104:107]
	v_mfma_f32_16x16x32_bf16 v[156:159], v[68:71], v[180:183], v[156:159]
	v_mfma_f32_16x16x32_bf16 v[152:155], v[76:79], v[180:183], v[152:155]
	v_mfma_f32_16x16x32_bf16 v[140:143], v[68:71], v[196:199], v[140:143]
	v_mfma_f32_16x16x32_bf16 v[136:139], v[76:79], v[196:199], v[136:139]
	v_mfma_f32_16x16x32_bf16 v[124:127], v[68:71], v[208:211], v[124:127]
	v_mfma_f32_16x16x32_bf16 v[120:123], v[76:79], v[208:211], v[120:123]
	v_mfma_f32_16x16x32_bf16 v[108:111], v[68:71], v[216:219], v[108:111]
	v_mfma_f32_16x16x32_bf16 v[104:107], v[76:79], v[216:219], v[104:107]
	s_setprio 0
	s_setprio 1
	v_mfma_f32_16x16x32_bf16 v[148:151], v[80:83], v[176:179], v[148:151]
	v_mfma_f32_16x16x32_bf16 v[144:147], v[88:91], v[176:179], v[144:147]
	v_mfma_f32_16x16x32_bf16 v[132:135], v[80:83], v[192:195], v[132:135]
	v_mfma_f32_16x16x32_bf16 v[128:131], v[88:91], v[192:195], v[128:131]
	v_mfma_f32_16x16x32_bf16 v[116:119], v[80:83], v[204:207], v[116:119]
	v_mfma_f32_16x16x32_bf16 v[112:115], v[88:91], v[204:207], v[112:115]
	v_mfma_f32_16x16x32_bf16 v[100:103], v[80:83], v[212:215], v[100:103]
	v_mfma_f32_16x16x32_bf16 v[96:99], v[88:91], v[212:215], v[96:99]
	v_mfma_f32_16x16x32_bf16 v[148:151], v[84:87], v[180:183], v[148:151]
	v_mfma_f32_16x16x32_bf16 v[144:147], v[92:95], v[180:183], v[144:147]
	v_mfma_f32_16x16x32_bf16 v[132:135], v[84:87], v[196:199], v[132:135]
	v_mfma_f32_16x16x32_bf16 v[128:131], v[92:95], v[196:199], v[128:131]
	v_mfma_f32_16x16x32_bf16 v[116:119], v[84:87], v[208:211], v[116:119]
	v_mfma_f32_16x16x32_bf16 v[112:115], v[92:95], v[208:211], v[112:115]
	v_mfma_f32_16x16x32_bf16 v[100:103], v[84:87], v[216:219], v[100:103]
	v_mfma_f32_16x16x32_bf16 v[96:99], v[92:95], v[216:219], v[96:99]
	s_setprio 0
	s_barrier
	s_add_i32 s22, s73, s3
	s_add_u32 s98, s40, s26
	s_addc_u32 s99, s41, s27
	s_mov_b32 m0, s22
	ds_read_b128 v[176:179], v190 offset:16384
	ds_read_b128 v[180:183], v190 offset:17408
	ds_read_b128 v[192:195], v190 offset:18432
	ds_read_b128 v[196:199], v190 offset:19456
	ds_read_b128 v[204:207], v190 offset:20480
	ds_read_b128 v[208:211], v190 offset:21504
	ds_read_b128 v[212:215], v190 offset:22528
	ds_read_b128 v[216:219], v190 offset:23552
	global_load_lds_dwordx4 v162, s[40:41]
	s_add_i32 m0, s22, 0x2000
	s_add_u32 s42, s40, 0x40000
	s_addc_u32 s43, s41, 0
	s_add_i32 s22, s77, s3
	global_load_lds_dwordx4 v166, s[40:41]
	s_mov_b32 m0, s22
	s_nop 0
	global_load_lds_dwordx4 v162, s[42:43]
	s_add_i32 m0, s22, 0x2000
	s_nop 0
	global_load_lds_dwordx4 v166, s[42:43]
	s_add_u32 s100, s64, s26
	s_addc_u32 s101, s65, s27
	s_mov_b32 m0, s21
	s_nop 0
	global_load_lds_dwordx4 v160, s[64:65]
	s_mov_b32 m0, s31
	s_nop 0
	global_load_lds_dwordx4 v164, s[64:65]
	s_waitcnt vmcnt(8)
	s_waitcnt lgkmcnt(0)
	s_barrier
	s_setprio 1
	s_waitcnt lgkmcnt(0)
	v_mfma_f32_16x16x32_bf16 v[60:63], v[64:67], v[176:179], v[60:63]
	v_mfma_f32_16x16x32_bf16 v[56:59], v[72:75], v[176:179], v[56:59]
	v_mfma_f32_16x16x32_bf16 v[44:47], v[64:67], v[192:195], v[44:47]
	v_mfma_f32_16x16x32_bf16 v[40:43], v[72:75], v[192:195], v[40:43]
	v_mfma_f32_16x16x32_bf16 v[28:31], v[64:67], v[204:207], v[28:31]
	v_mfma_f32_16x16x32_bf16 v[24:27], v[72:75], v[204:207], v[24:27]
	v_mfma_f32_16x16x32_bf16 v[12:15], v[64:67], v[212:215], v[12:15]
	v_mfma_f32_16x16x32_bf16 v[8:11], v[72:75], v[212:215], v[8:11]
	v_mfma_f32_16x16x32_bf16 v[60:63], v[68:71], v[180:183], v[60:63]
	v_mfma_f32_16x16x32_bf16 v[56:59], v[76:79], v[180:183], v[56:59]
	v_mfma_f32_16x16x32_bf16 v[44:47], v[68:71], v[196:199], v[44:47]
	v_mfma_f32_16x16x32_bf16 v[40:43], v[76:79], v[196:199], v[40:43]
	v_mfma_f32_16x16x32_bf16 v[28:31], v[68:71], v[208:211], v[28:31]
	v_mfma_f32_16x16x32_bf16 v[24:27], v[76:79], v[208:211], v[24:27]
	v_mfma_f32_16x16x32_bf16 v[12:15], v[68:71], v[216:219], v[12:15]
	v_mfma_f32_16x16x32_bf16 v[8:11], v[76:79], v[216:219], v[8:11]
	s_setprio 0
	s_setprio 1
	v_mfma_f32_16x16x32_bf16 v[52:55], v[80:83], v[176:179], v[52:55]
	v_mfma_f32_16x16x32_bf16 v[48:51], v[88:91], v[176:179], v[48:51]
	v_mfma_f32_16x16x32_bf16 v[36:39], v[80:83], v[192:195], v[36:39]
	v_mfma_f32_16x16x32_bf16 v[32:35], v[88:91], v[192:195], v[32:35]
	v_mfma_f32_16x16x32_bf16 v[20:23], v[80:83], v[204:207], v[20:23]
	v_mfma_f32_16x16x32_bf16 v[16:19], v[88:91], v[204:207], v[16:19]
	v_mfma_f32_16x16x32_bf16 v[4:7], v[80:83], v[212:215], v[4:7]
	v_mfma_f32_16x16x32_bf16 v[0:3], v[88:91], v[212:215], v[0:3]
	v_mfma_f32_16x16x32_bf16 v[52:55], v[84:87], v[180:183], v[52:55]
	v_mfma_f32_16x16x32_bf16 v[48:51], v[92:95], v[180:183], v[48:51]
	v_mfma_f32_16x16x32_bf16 v[36:39], v[84:87], v[196:199], v[36:39]
	v_mfma_f32_16x16x32_bf16 v[32:35], v[92:95], v[196:199], v[32:35]
	v_mfma_f32_16x16x32_bf16 v[20:23], v[84:87], v[208:211], v[20:23]
	v_mfma_f32_16x16x32_bf16 v[16:19], v[92:95], v[208:211], v[16:19]
	v_mfma_f32_16x16x32_bf16 v[4:7], v[84:87], v[216:219], v[4:7]
	v_mfma_f32_16x16x32_bf16 v[0:3], v[92:95], v[216:219], v[0:3]
	s_setprio 0
	s_barrier
; #define PG8_STAGE(bufoff, gbase, voff) do { _Pragma("unroll") for (int _i = 0; _i < 2; ++_i) \
;         __builtin_amdgcn_global_load_lds((const unsigned*)((const char*)(gbase) + (voff)[_i]), (LAS unsigned*)(lds + (bufoff) + ldsw + _i * 8192), 16, 0, 0); } while (0)
; #define PG8_LDA(dst, b, h) do { _Pragma("unroll") for (int m = 0; m < 4; ++m) _Pragma("unroll") for (int k = 0; k < 2; ++k) dst[m][k] = *(const LAS bf16x8*)(lds + PG8_SA(b, h) + aoff + m * 2048 + k * 1024); } while (0)
; #define PG8_LDB(dst, b, h) do { _Pragma("unroll") for (int n = 0; n < 2; ++n) _Pragma("unroll") for (int k = 0; k < 2; ++k) dst[n][k] = *(const LAS bf16x8*)(lds + PG8_SB(b, h) + boff + n * 2048 + k * 1024); } while (0)
; #define PG8_MMA(ai, bj, At, Bt) do { __builtin_amdgcn_s_setprio(1); _Pragma("unroll") for (int m = 0; m < 4; ++m) _Pragma("unroll") for (int n = 0; n < 2; ++n) _Pragma("unroll") for (int k = 0; k < 2; ++k) \
;         acc[ai][bj][m][n] = __builtin_amdgcn_mfma_f32_16x16x32_bf16(Bt[n][k], At[m][k], acc[ai][bj][m][n], 0, 0, 0); __builtin_amdgcn_s_setprio(0); } while (0)
; #define PG8_WAIT_V(n) asm volatile("s_waitcnt vmcnt(" #n ")" ::: "memory")
; #define PG8_WAIT_L(n) asm volatile("s_waitcnt lgkmcnt(" #n ")" ::: "memory")
; #define PG8_BAR __builtin_amdgcn_s_barrier()
; #define PG8_SCHED __builtin_amdgcn_sched_barrier(0)
; template <class Epi, class Sched, bool ALIGN_EPI>
; __device__ __forceinline__ void gemm_phase(LAS unsigned char* lds, const GemmDesc g, const Sched& S, const Epi& E) {
;     ...
;             PG8_LDB(B0, 1, 0); PG8_LDB(B1, 1, 1); PG8_SCHED; PG8_LDA(At, 1, 0); PG8_STAGE(PG8_SA(0, 1), a2 + hstepA, voffA);
;             PG8_WAIT_V(8); PG8_WAIT_L(0); PG8_BAR; PG8_MMA(0, 0, At, B0); PG8_MMA(0, 1, At, B1); PG8_BAR; PG8_SCHED;
;             PG8_LDA(At, 1, 1); PG8_STAGE(PG8_SB(1, 0), b3, voffB); PG8_STAGE(PG8_SB(1, 1), b3 + hstepB, voffB); PG8_STAGE(PG8_SA(1, 0), a3, voffA);
;             PG8_WAIT_V(8); PG8_WAIT_L(0); PG8_BAR; PG8_MMA(1, 0, At, B0); PG8_MMA(1, 1, At, B1); PG8_BAR; PG8_SCHED;
;         }
	s_add_i32 s22, 0, 0x18000
	s_add_i32 s35, 0, 0x1c000
	v_add_u32_e32 v76, s22, v187
	v_add_u32_e32 v92, s35, v187
	ds_read_b128 v[64:67], v76
	ds_read_b128 v[68:71], v76 offset:1024
	ds_read_b128 v[72:75], v76 offset:2048
	ds_read_b128 v[76:79], v76 offset:3072
	ds_read_b128 v[80:83], v92
	ds_read_b128 v[84:87], v92 offset:1024
	ds_read_b128 v[88:91], v92 offset:2048
	ds_read_b128 v[92:95], v92 offset:3072
	s_add_u32 s42, s64, 0x40000
	s_addc_u32 s43, s65, 0
	s_mov_b32 m0, s66
	ds_read_b128 v[176:179], v190 offset:32768
	ds_read_b128 v[180:183], v190 offset:33792
	ds_read_b128 v[192:195], v190 offset:34816
	ds_read_b128 v[196:199], v190 offset:35840
	ds_read_b128 v[204:207], v190 offset:36864
	ds_read_b128 v[208:211], v190 offset:37888
	ds_read_b128 v[212:215], v190 offset:38912
	ds_read_b128 v[216:219], v190 offset:39936
	global_load_lds_dwordx4 v160, s[42:43]
	s_mov_b32 m0, s67
	s_nop 0
	global_load_lds_dwordx4 v164, s[42:43]
	s_waitcnt vmcnt(8)
	s_waitcnt lgkmcnt(0)
	s_barrier
	s_setprio 1
	s_waitcnt lgkmcnt(0)
	v_mfma_f32_16x16x32_bf16 v[156:159], v[64:67], v[176:179], v[156:159]
	v_mfma_f32_16x16x32_bf16 v[152:155], v[72:75], v[176:179], v[152:155]
	v_mfma_f32_16x16x32_bf16 v[140:143], v[64:67], v[192:195], v[140:143]
	v_mfma_f32_16x16x32_bf16 v[136:139], v[72:75], v[192:195], v[136:139]
	v_mfma_f32_16x16x32_bf16 v[124:127], v[64:67], v[204:207], v[124:127]
	v_mfma_f32_16x16x32_bf16 v[120:123], v[72:75], v[204:207], v[120:123]
	v_mfma_f32_16x16x32_bf16 v[108:111], v[64:67], v[212:215], v[108:111]
	v_mfma_f32_16x16x32_bf16 v[104:107], v[72:75], v[212:215], v[104:107]
	v_mfma_f32_16x16x32_bf16 v[156:159], v[68:71], v[180:183], v[156:159]
	v_mfma_f32_16x16x32_bf16 v[152:155], v[76:79], v[180:183], v[152:155]
	v_mfma_f32_16x16x32_bf16 v[140:143], v[68:71], v[196:199], v[140:143]
	v_mfma_f32_16x16x32_bf16 v[136:139], v[76:79], v[196:199], v[136:139]
	v_mfma_f32_16x16x32_bf16 v[124:127], v[68:71], v[208:211], v[124:127]
	v_mfma_f32_16x16x32_bf16 v[120:123], v[76:79], v[208:211], v[120:123]
	v_mfma_f32_16x16x32_bf16 v[108:111], v[68:71], v[216:219], v[108:111]
	v_mfma_f32_16x16x32_bf16 v[104:107], v[76:79], v[216:219], v[104:107]
	s_setprio 0
	s_setprio 1
	v_mfma_f32_16x16x32_bf16 v[148:151], v[80:83], v[176:179], v[148:151]
	v_mfma_f32_16x16x32_bf16 v[144:147], v[88:91], v[176:179], v[144:147]
	v_mfma_f32_16x16x32_bf16 v[132:135], v[80:83], v[192:195], v[132:135]
	v_mfma_f32_16x16x32_bf16 v[128:131], v[88:91], v[192:195], v[128:131]
	v_mfma_f32_16x16x32_bf16 v[116:119], v[80:83], v[204:207], v[116:119]
	v_mfma_f32_16x16x32_bf16 v[112:115], v[88:91], v[204:207], v[112:115]
	v_mfma_f32_16x16x32_bf16 v[100:103], v[80:83], v[212:215], v[100:103]
	v_mfma_f32_16x16x32_bf16 v[96:99], v[88:91], v[212:215], v[96:99]
	v_mfma_f32_16x16x32_bf16 v[148:151], v[84:87], v[180:183], v[148:151]
	v_mfma_f32_16x16x32_bf16 v[144:147], v[92:95], v[180:183], v[144:147]
	v_mfma_f32_16x16x32_bf16 v[132:135], v[84:87], v[196:199], v[132:135]
	v_mfma_f32_16x16x32_bf16 v[128:131], v[92:95], v[196:199], v[128:131]
	v_mfma_f32_16x16x32_bf16 v[116:119], v[84:87], v[208:211], v[116:119]
	v_mfma_f32_16x16x32_bf16 v[112:115], v[92:95], v[208:211], v[112:115]
	v_mfma_f32_16x16x32_bf16 v[100:103], v[84:87], v[216:219], v[100:103]
	v_mfma_f32_16x16x32_bf16 v[96:99], v[92:95], v[216:219], v[96:99]
	s_setprio 0
	s_barrier
	s_add_i32 s22, s22, s3
	s_mov_b32 m0, s22
	ds_read_b128 v[176:179], v190 offset:49152
	ds_read_b128 v[180:183], v190 offset:50176
	ds_read_b128 v[192:195], v190 offset:51200
	ds_read_b128 v[196:199], v190 offset:52224
	ds_read_b128 v[204:207], v190 offset:53248
	ds_read_b128 v[208:211], v190 offset:54272
	ds_read_b128 v[212:215], v190 offset:55296
	ds_read_b128 v[216:219], v190 offset:56320
	global_load_lds_dwordx4 v162, s[98:99]
	s_add_i32 m0, s22, 0x2000
	s_add_u32 s40, s40, 0x40080
	s_addc_u32 s41, s41, 0
	s_add_i32 s22, s35, s3
	global_load_lds_dwordx4 v166, s[98:99]
	s_mov_b32 m0, s22
	s_nop 0
	global_load_lds_dwordx4 v162, s[40:41]
	s_add_i32 m0, s22, 0x2000
	s_nop 0
	global_load_lds_dwordx4 v166, s[40:41]
	s_mov_b32 m0, s71
	s_nop 0
	global_load_lds_dwordx4 v160, s[100:101]
	s_mov_b32 m0, s72
	s_nop 0
	global_load_lds_dwordx4 v164, s[100:101]
	s_waitcnt vmcnt(8)
	s_waitcnt lgkmcnt(0)
	s_barrier
	s_setprio 1
	s_waitcnt lgkmcnt(0)
	v_mfma_f32_16x16x32_bf16 v[60:63], v[64:67], v[176:179], v[60:63]
	v_mfma_f32_16x16x32_bf16 v[56:59], v[72:75], v[176:179], v[56:59]
	v_mfma_f32_16x16x32_bf16 v[44:47], v[64:67], v[192:195], v[44:47]
	v_mfma_f32_16x16x32_bf16 v[40:43], v[72:75], v[192:195], v[40:43]
	v_mfma_f32_16x16x32_bf16 v[28:31], v[64:67], v[204:207], v[28:31]
	v_mfma_f32_16x16x32_bf16 v[24:27], v[72:75], v[204:207], v[24:27]
	v_mfma_f32_16x16x32_bf16 v[12:15], v[64:67], v[212:215], v[12:15]
	v_mfma_f32_16x16x32_bf16 v[8:11], v[72:75], v[212:215], v[8:11]
	v_mfma_f32_16x16x32_bf16 v[60:63], v[68:71], v[180:183], v[60:63]
	v_mfma_f32_16x16x32_bf16 v[56:59], v[76:79], v[180:183], v[56:59]
	v_mfma_f32_16x16x32_bf16 v[44:47], v[68:71], v[196:199], v[44:47]
	v_mfma_f32_16x16x32_bf16 v[40:43], v[76:79], v[196:199], v[40:43]
	v_mfma_f32_16x16x32_bf16 v[28:31], v[68:71], v[208:211], v[28:31]
	v_mfma_f32_16x16x32_bf16 v[24:27], v[76:79], v[208:211], v[24:27]
	v_mfma_f32_16x16x32_bf16 v[12:15], v[68:71], v[216:219], v[12:15]
	v_mfma_f32_16x16x32_bf16 v[8:11], v[76:79], v[216:219], v[8:11]
	s_setprio 0
	s_setprio 1
	v_mfma_f32_16x16x32_bf16 v[52:55], v[80:83], v[176:179], v[52:55]
	v_mfma_f32_16x16x32_bf16 v[48:51], v[88:91], v[176:179], v[48:51]
	v_mfma_f32_16x16x32_bf16 v[36:39], v[80:83], v[192:195], v[36:39]
	v_mfma_f32_16x16x32_bf16 v[32:35], v[88:91], v[192:195], v[32:35]
	v_mfma_f32_16x16x32_bf16 v[20:23], v[80:83], v[204:207], v[20:23]
	v_mfma_f32_16x16x32_bf16 v[16:19], v[88:91], v[204:207], v[16:19]
	v_mfma_f32_16x16x32_bf16 v[4:7], v[80:83], v[212:215], v[4:7]
	v_mfma_f32_16x16x32_bf16 v[0:3], v[88:91], v[212:215], v[0:3]
	v_mfma_f32_16x16x32_bf16 v[52:55], v[84:87], v[180:183], v[52:55]
	v_mfma_f32_16x16x32_bf16 v[48:51], v[92:95], v[180:183], v[48:51]
	v_mfma_f32_16x16x32_bf16 v[36:39], v[84:87], v[196:199], v[36:39]
	v_mfma_f32_16x16x32_bf16 v[32:35], v[92:95], v[196:199], v[32:35]
	v_mfma_f32_16x16x32_bf16 v[20:23], v[84:87], v[208:211], v[20:23]
	v_mfma_f32_16x16x32_bf16 v[16:19], v[92:95], v[208:211], v[16:19]
	v_mfma_f32_16x16x32_bf16 v[4:7], v[84:87], v[216:219], v[4:7]
	v_mfma_f32_16x16x32_bf16 v[0:3], v[92:95], v[216:219], v[0:3]
	s_setprio 0
	s_barrier
	s_add_i32 s7, s7, 2
	s_add_u32 s10, s10, 0x100
	s_addc_u32 s11, s11, 0
	s_add_u32 s5, s5, 0x100
	s_addc_u32 s6, s6, 0
	s_cmp_gt_u32 s7, 13
	s_cbranch_scc0 .LBB0_1257
	s_and_b64 vcc, exec, s[28:29]
	s_cbranch_vccz .LBB0_1260
	s_barrier

; #define PG8_STAGE(bufoff, gbase, voff) do { _Pragma("unroll") for (int _i = 0; _i < 2; ++_i) \
;         __builtin_amdgcn_global_load_lds((const unsigned*)((const char*)(gbase) + (voff)[_i]), (LAS unsigned*)(lds + (bufoff) + ldsw + _i * 8192), 16, 0, 0); } while (0)
; #define PG8_LDA(dst, b, h) do { _Pragma("unroll") for (int m = 0; m < 4; ++m) _Pragma("unroll") for (int k = 0; k < 2; ++k) dst[m][k] = *(const LAS bf16x8*)(lds + PG8_SA(b, h) + aoff + m * 2048 + k * 1024); } while (0)
; #define PG8_LDB(dst, b, h) do { _Pragma("unroll") for (int n = 0; n < 2; ++n) _Pragma("unroll") for (int k = 0; k < 2; ++k) dst[n][k] = *(const LAS bf16x8*)(lds + PG8_SB(b, h) + boff + n * 2048 + k * 1024); } while (0)
; #define PG8_MMA(ai, bj, At, Bt) do { __builtin_amdgcn_s_setprio(1); _Pragma("unroll") for (int m = 0; m < 4; ++m) _Pragma("unroll") for (int n = 0; n < 2; ++n) _Pragma("unroll") for (int k = 0; k < 2; ++k) \
;         acc[ai][bj][m][n] = __builtin_amdgcn_mfma_f32_16x16x32_bf16(Bt[n][k], At[m][k], acc[ai][bj][m][n], 0, 0, 0); __builtin_amdgcn_s_setprio(0); } while (0)
; #define PG8_WAIT_V(n) asm volatile("s_waitcnt vmcnt(" #n ")" ::: "memory")
; #define PG8_WAIT_L(n) asm volatile("s_waitcnt lgkmcnt(" #n ")" ::: "memory")
; #define PG8_BAR __builtin_amdgcn_s_barrier()
; #define PG8_SCHED __builtin_amdgcn_sched_barrier(0)
; template <class Epi, class Sched, bool ALIGN_EPI>
; __device__ __forceinline__ void gemm_phase(LAS unsigned char* lds, const GemmDesc g, const Sched& S, const Epi& E) {
;     ...
;             const bool last = (t == nt - 2);
;             const char* a1 = cA + (size_t)(t + 1) * kstep;
;             const char* a2 = last ? nA : cA + (size_t)(t + 2) * kstep; const char* b2 = last ? nB : cB + (size_t)(t + 2) * kstep;
;             const char* a3 = a2 + kstep; const char* b3 = b2 + kstep;
;             PG8_LDB(B0, 0, 0); PG8_LDB(B1, 0, 1); PG8_SCHED; PG8_LDA(At, 0, 0); PG8_STAGE(PG8_SA(1, 1), a1 + hstepA, voffA);
;             PG8_WAIT_V(8); PG8_WAIT_L(0); PG8_BAR; PG8_MMA(0, 0, At, B0); PG8_MMA(0, 1, At, B1); PG8_BAR; PG8_SCHED;
;             PG8_LDA(At, 0, 1); PG8_STAGE(PG8_SB(0, 0), b2, voffB); PG8_STAGE(PG8_SB(0, 1), b2 + hstepB, voffB); PG8_STAGE(PG8_SA(0, 0), a2, voffA);
;             PG8_WAIT_V(8); PG8_WAIT_L(0); PG8_BAR; PG8_MMA(1, 0, At, B0); PG8_MMA(1, 1, At, B1); PG8_BAR; PG8_SCHED;
.LBB0_1378:
	ds_read_b128 v[128:131], v181
	ds_read_b128 v[132:135], v181 offset:1024
	ds_read_b128 v[136:139], v181 offset:2048
	ds_read_b128 v[140:143], v181 offset:3072
	ds_read_b128 v[144:147], v182
	ds_read_b128 v[148:151], v182 offset:1024
	ds_read_b128 v[152:155], v182 offset:2048
	ds_read_b128 v[156:159], v182 offset:3072
	s_add_u32 s40, s38, 0xfffc0080
	s_addc_u32 s41, s39, -1
	s_cmp_eq_u32 s70, 12
	s_cselect_b32 s47, s21, s41
	s_cselect_b32 s46, s27, s40
	s_cselect_b32 s41, s25, s69
	s_cselect_b32 s40, s67, s68
	s_add_i32 m0, s7, 0xc000
	ds_read_b128 v[174:177], v183
	ds_read_b128 v[184:187], v183 offset:1024
	ds_read_b128 v[188:191], v183 offset:2048
	ds_read_b128 v[192:195], v183 offset:3072
	ds_read_b128 v[196:199], v183 offset:4096
	ds_read_b128 v[204:207], v183 offset:5120
	ds_read_b128 v[208:211], v183 offset:6144
	ds_read_b128 v[212:215], v183 offset:7168
	global_load_lds_dwordx4 v168, s[38:39]
	s_add_i32 m0, s7, 0xe000
	s_nop 0
	global_load_lds_dwordx4 v170, s[38:39]
	s_waitcnt vmcnt(8)
	s_waitcnt lgkmcnt(0)
	s_barrier
	s_setprio 1
	s_waitcnt lgkmcnt(0)
	v_mfma_f32_16x16x32_bf16 v[124:127], v[128:131], v[174:177], v[124:127]
	v_mfma_f32_16x16x32_bf16 v[120:123], v[136:139], v[174:177], v[120:123]
	v_mfma_f32_16x16x32_bf16 v[108:111], v[128:131], v[188:191], v[108:111]
	v_mfma_f32_16x16x32_bf16 v[104:107], v[136:139], v[188:191], v[104:107]
	v_mfma_f32_16x16x32_bf16 v[92:95], v[128:131], v[196:199], v[92:95]
	v_mfma_f32_16x16x32_bf16 v[88:91], v[136:139], v[196:199], v[88:91]
	v_mfma_f32_16x16x32_bf16 v[76:79], v[128:131], v[208:211], v[76:79]
	v_mfma_f32_16x16x32_bf16 v[72:75], v[136:139], v[208:211], v[72:75]
	v_mfma_f32_16x16x32_bf16 v[124:127], v[132:135], v[184:187], v[124:127]
	v_mfma_f32_16x16x32_bf16 v[120:123], v[140:143], v[184:187], v[120:123]
	v_mfma_f32_16x16x32_bf16 v[108:111], v[132:135], v[192:195], v[108:111]
	v_mfma_f32_16x16x32_bf16 v[104:107], v[140:143], v[192:195], v[104:107]
	v_mfma_f32_16x16x32_bf16 v[92:95], v[132:135], v[204:207], v[92:95]
	v_mfma_f32_16x16x32_bf16 v[88:91], v[140:143], v[204:207], v[88:91]
	v_mfma_f32_16x16x32_bf16 v[76:79], v[132:135], v[212:215], v[76:79]
	v_mfma_f32_16x16x32_bf16 v[72:75], v[140:143], v[212:215], v[72:75]
	s_setprio 0
	s_setprio 1
	v_mfma_f32_16x16x32_bf16 v[116:119], v[144:147], v[174:177], v[116:119]
	v_mfma_f32_16x16x32_bf16 v[112:115], v[152:155], v[174:177], v[112:115]
	v_mfma_f32_16x16x32_bf16 v[100:103], v[144:147], v[188:191], v[100:103]
	v_mfma_f32_16x16x32_bf16 v[96:99], v[152:155], v[188:191], v[96:99]
	v_mfma_f32_16x16x32_bf16 v[84:87], v[144:147], v[196:199], v[84:87]
	v_mfma_f32_16x16x32_bf16 v[80:83], v[152:155], v[196:199], v[80:83]
	v_mfma_f32_16x16x32_bf16 v[68:71], v[144:147], v[208:211], v[68:71]
	v_mfma_f32_16x16x32_bf16 v[64:67], v[152:155], v[208:211], v[64:67]
	v_mfma_f32_16x16x32_bf16 v[116:119], v[148:151], v[184:187], v[116:119]
	v_mfma_f32_16x16x32_bf16 v[112:115], v[156:159], v[184:187], v[112:115]
	v_mfma_f32_16x16x32_bf16 v[100:103], v[148:151], v[192:195], v[100:103]
	v_mfma_f32_16x16x32_bf16 v[96:99], v[156:159], v[192:195], v[96:99]
	v_mfma_f32_16x16x32_bf16 v[84:87], v[148:151], v[204:207], v[84:87]
	v_mfma_f32_16x16x32_bf16 v[80:83], v[156:159], v[204:207], v[80:83]
	v_mfma_f32_16x16x32_bf16 v[68:71], v[148:151], v[212:215], v[68:71]
	v_mfma_f32_16x16x32_bf16 v[64:67], v[156:159], v[212:215], v[64:67]
	s_setprio 0
	s_barrier
	s_add_i32 s71, s64, s6
	s_add_u32 s98, s40, s14
	s_addc_u32 s99, s41, s15
	s_mov_b32 m0, s71
	ds_read_b128 v[174:177], v183 offset:16384
	ds_read_b128 v[184:187], v183 offset:17408
	ds_read_b128 v[188:191], v183 offset:18432
	ds_read_b128 v[192:195], v183 offset:19456
	ds_read_b128 v[196:199], v183 offset:20480
	ds_read_b128 v[204:207], v183 offset:21504
	ds_read_b128 v[208:211], v183 offset:22528
	ds_read_b128 v[212:215], v183 offset:23552
	global_load_lds_dwordx4 v162, s[40:41]
	s_add_i32 m0, s71, 0x2000
	s_add_u32 s72, s40, 0x40000
	s_addc_u32 s73, s41, 0
	s_add_i32 s71, s65, s6
	global_load_lds_dwordx4 v166, s[40:41]
	s_mov_b32 m0, s71
	s_nop 0
	global_load_lds_dwordx4 v162, s[72:73]
	s_add_i32 m0, s71, 0x2000
	s_nop 0
	global_load_lds_dwordx4 v166, s[72:73]
	s_add_u32 s100, s46, s14
	s_addc_u32 s101, s47, s15
	s_mov_b32 m0, s7
	s_nop 0
	global_load_lds_dwordx4 v160, s[46:47]
	s_mov_b32 m0, s11
	s_nop 0
	global_load_lds_dwordx4 v164, s[46:47]
	s_waitcnt vmcnt(8)
	s_waitcnt lgkmcnt(0)
	s_barrier
	s_setprio 1
	s_waitcnt lgkmcnt(0)
	v_mfma_f32_16x16x32_bf16 v[60:63], v[128:131], v[174:177], v[60:63]
	v_mfma_f32_16x16x32_bf16 v[56:59], v[136:139], v[174:177], v[56:59]
	v_mfma_f32_16x16x32_bf16 v[44:47], v[128:131], v[188:191], v[44:47]
	v_mfma_f32_16x16x32_bf16 v[40:43], v[136:139], v[188:191], v[40:43]
	v_mfma_f32_16x16x32_bf16 v[28:31], v[128:131], v[196:199], v[28:31]
	v_mfma_f32_16x16x32_bf16 v[24:27], v[136:139], v[196:199], v[24:27]
	v_mfma_f32_16x16x32_bf16 v[12:15], v[128:131], v[208:211], v[12:15]
	v_mfma_f32_16x16x32_bf16 v[8:11], v[136:139], v[208:211], v[8:11]
	v_mfma_f32_16x16x32_bf16 v[60:63], v[132:135], v[184:187], v[60:63]
	v_mfma_f32_16x16x32_bf16 v[56:59], v[140:143], v[184:187], v[56:59]
	v_mfma_f32_16x16x32_bf16 v[44:47], v[132:135], v[192:195], v[44:47]
	v_mfma_f32_16x16x32_bf16 v[40:43], v[140:143], v[192:195], v[40:43]
	v_mfma_f32_16x16x32_bf16 v[28:31], v[132:135], v[204:207], v[28:31]
	v_mfma_f32_16x16x32_bf16 v[24:27], v[140:143], v[204:207], v[24:27]
	v_mfma_f32_16x16x32_bf16 v[12:15], v[132:135], v[212:215], v[12:15]
	v_mfma_f32_16x16x32_bf16 v[8:11], v[140:143], v[212:215], v[8:11]
	s_setprio 0
	s_setprio 1
	v_mfma_f32_16x16x32_bf16 v[52:55], v[144:147], v[174:177], v[52:55]
	v_mfma_f32_16x16x32_bf16 v[48:51], v[152:155], v[174:177], v[48:51]
	v_mfma_f32_16x16x32_bf16 v[36:39], v[144:147], v[188:191], v[36:39]
	v_mfma_f32_16x16x32_bf16 v[32:35], v[152:155], v[188:191], v[32:35]
	v_mfma_f32_16x16x32_bf16 v[20:23], v[144:147], v[196:199], v[20:23]
	v_mfma_f32_16x16x32_bf16 v[16:19], v[152:155], v[196:199], v[16:19]
	v_mfma_f32_16x16x32_bf16 v[4:7], v[144:147], v[208:211], v[4:7]
	v_mfma_f32_16x16x32_bf16 v[0:3], v[152:155], v[208:211], v[0:3]
	v_mfma_f32_16x16x32_bf16 v[52:55], v[148:151], v[184:187], v[52:55]
	v_mfma_f32_16x16x32_bf16 v[48:51], v[156:159], v[184:187], v[48:51]
	v_mfma_f32_16x16x32_bf16 v[36:39], v[148:151], v[192:195], v[36:39]
	v_mfma_f32_16x16x32_bf16 v[32:35], v[156:159], v[192:195], v[32:35]
	v_mfma_f32_16x16x32_bf16 v[20:23], v[148:151], v[204:207], v[20:23]
	v_mfma_f32_16x16x32_bf16 v[16:19], v[156:159], v[204:207], v[16:19]
	v_mfma_f32_16x16x32_bf16 v[4:7], v[148:151], v[212:215], v[4:7]
	v_mfma_f32_16x16x32_bf16 v[0:3], v[156:159], v[212:215], v[0:3]
	s_setprio 0
	s_barrier
; #define PG8_STAGE(bufoff, gbase, voff) do { _Pragma("unroll") for (int _i = 0; _i < 2; ++_i) \
;         __builtin_amdgcn_global_load_lds((const unsigned*)((const char*)(gbase) + (voff)[_i]), (LAS unsigned*)(lds + (bufoff) + ldsw + _i * 8192), 16, 0, 0); } while (0)
; #define PG8_LDA(dst, b, h) do { _Pragma("unroll") for (int m = 0; m < 4; ++m) _Pragma("unroll") for (int k = 0; k < 2; ++k) dst[m][k] = *(const LAS bf16x8*)(lds + PG8_SA(b, h) + aoff + m * 2048 + k * 1024); } while (0)
; #define PG8_LDB(dst, b, h) do { _Pragma("unroll") for (int n = 0; n < 2; ++n) _Pragma("unroll") for (int k = 0; k < 2; ++k) dst[n][k] = *(const LAS bf16x8*)(lds + PG8_SB(b, h) + boff + n * 2048 + k * 1024); } while (0)
; #define PG8_MMA(ai, bj, At, Bt) do { __builtin_amdgcn_s_setprio(1); _Pragma("unroll") for (int m = 0; m < 4; ++m) _Pragma("unroll") for (int n = 0; n < 2; ++n) _Pragma("unroll") for (int k = 0; k < 2; ++k) \
;         acc[ai][bj][m][n] = __builtin_amdgcn_mfma_f32_16x16x32_bf16(Bt[n][k], At[m][k], acc[ai][bj][m][n], 0, 0, 0); __builtin_amdgcn_s_setprio(0); } while (0)
; #define PG8_WAIT_V(n) asm volatile("s_waitcnt vmcnt(" #n ")" ::: "memory")
; #define PG8_WAIT_L(n) asm volatile("s_waitcnt lgkmcnt(" #n ")" ::: "memory")
; #define PG8_BAR __builtin_amdgcn_s_barrier()
; #define PG8_SCHED __builtin_amdgcn_sched_barrier(0)
; template <class Epi, class Sched, bool ALIGN_EPI>
; __device__ __forceinline__ void gemm_phase(LAS unsigned char* lds, const GemmDesc g, const Sched& S, const Epi& E) {
;     ...
;             PG8_LDB(B0, 1, 0); PG8_LDB(B1, 1, 1); PG8_SCHED; PG8_LDA(At, 1, 0); PG8_STAGE(PG8_SA(0, 1), a2 + hstepA, voffA);
;             PG8_WAIT_V(8); PG8_WAIT_L(0); PG8_BAR; PG8_MMA(0, 0, At, B0); PG8_MMA(0, 1, At, B1); PG8_BAR; PG8_SCHED;
;             PG8_LDA(At, 1, 1); PG8_STAGE(PG8_SB(1, 0), b3, voffB); PG8_STAGE(PG8_SB(1, 1), b3 + hstepB, voffB); PG8_STAGE(PG8_SA(1, 0), a3, voffA);
;             PG8_WAIT_V(8); PG8_WAIT_L(0); PG8_BAR; PG8_MMA(1, 0, At, B0); PG8_MMA(1, 1, At, B1); PG8_BAR; PG8_SCHED;
;         }
	s_add_i32 s71, 0, 0x18000
	s_add_i32 s72, 0, 0x1c000
	v_add_u32_e32 v140, s71, v180
	v_add_u32_e32 v156, s72, v180
	ds_read_b128 v[128:131], v140
	ds_read_b128 v[132:135], v140 offset:1024
	ds_read_b128 v[136:139], v140 offset:2048
	ds_read_b128 v[140:143], v140 offset:3072
	ds_read_b128 v[144:147], v156
	ds_read_b128 v[148:151], v156 offset:1024
	ds_read_b128 v[152:155], v156 offset:2048
	ds_read_b128 v[156:159], v156 offset:3072
	s_add_u32 s46, s46, 0x40000
	s_addc_u32 s47, s47, 0
	s_mov_b32 m0, s37
	ds_read_b128 v[174:177], v183 offset:32768
	ds_read_b128 v[184:187], v183 offset:33792
	ds_read_b128 v[188:191], v183 offset:34816
	ds_read_b128 v[192:195], v183 offset:35840
	ds_read_b128 v[196:199], v183 offset:36864
	ds_read_b128 v[204:207], v183 offset:37888
	ds_read_b128 v[208:211], v183 offset:38912
	ds_read_b128 v[212:215], v183 offset:39936
	global_load_lds_dwordx4 v160, s[46:47]
	s_mov_b32 m0, s42
	s_nop 0
	global_load_lds_dwordx4 v164, s[46:47]
	s_waitcnt vmcnt(8)
	s_waitcnt lgkmcnt(0)
	s_barrier
	s_setprio 1
	s_waitcnt lgkmcnt(0)
	v_mfma_f32_16x16x32_bf16 v[124:127], v[128:131], v[174:177], v[124:127]
	v_mfma_f32_16x16x32_bf16 v[120:123], v[136:139], v[174:177], v[120:123]
	v_mfma_f32_16x16x32_bf16 v[108:111], v[128:131], v[188:191], v[108:111]
	v_mfma_f32_16x16x32_bf16 v[104:107], v[136:139], v[188:191], v[104:107]
	v_mfma_f32_16x16x32_bf16 v[92:95], v[128:131], v[196:199], v[92:95]
	v_mfma_f32_16x16x32_bf16 v[88:91], v[136:139], v[196:199], v[88:91]
	v_mfma_f32_16x16x32_bf16 v[76:79], v[128:131], v[208:211], v[76:79]
	v_mfma_f32_16x16x32_bf16 v[72:75], v[136:139], v[208:211], v[72:75]
	v_mfma_f32_16x16x32_bf16 v[124:127], v[132:135], v[184:187], v[124:127]
	v_mfma_f32_16x16x32_bf16 v[120:123], v[140:143], v[184:187], v[120:123]
	v_mfma_f32_16x16x32_bf16 v[108:111], v[132:135], v[192:195], v[108:111]
	v_mfma_f32_16x16x32_bf16 v[104:107], v[140:143], v[192:195], v[104:107]
	v_mfma_f32_16x16x32_bf16 v[92:95], v[132:135], v[204:207], v[92:95]
	v_mfma_f32_16x16x32_bf16 v[88:91], v[140:143], v[204:207], v[88:91]
	v_mfma_f32_16x16x32_bf16 v[76:79], v[132:135], v[212:215], v[76:79]
	v_mfma_f32_16x16x32_bf16 v[72:75], v[140:143], v[212:215], v[72:75]
	s_setprio 0
	s_setprio 1
	v_mfma_f32_16x16x32_bf16 v[116:119], v[144:147], v[174:177], v[116:119]
	v_mfma_f32_16x16x32_bf16 v[112:115], v[152:155], v[174:177], v[112:115]
	v_mfma_f32_16x16x32_bf16 v[100:103], v[144:147], v[188:191], v[100:103]
	v_mfma_f32_16x16x32_bf16 v[96:99], v[152:155], v[188:191], v[96:99]
	v_mfma_f32_16x16x32_bf16 v[84:87], v[144:147], v[196:199], v[84:87]
	v_mfma_f32_16x16x32_bf16 v[80:83], v[152:155], v[196:199], v[80:83]
	v_mfma_f32_16x16x32_bf16 v[68:71], v[144:147], v[208:211], v[68:71]
	v_mfma_f32_16x16x32_bf16 v[64:67], v[152:155], v[208:211], v[64:67]
	v_mfma_f32_16x16x32_bf16 v[116:119], v[148:151], v[184:187], v[116:119]
	v_mfma_f32_16x16x32_bf16 v[112:115], v[156:159], v[184:187], v[112:115]
	v_mfma_f32_16x16x32_bf16 v[100:103], v[148:151], v[192:195], v[100:103]
	v_mfma_f32_16x16x32_bf16 v[96:99], v[156:159], v[192:195], v[96:99]
	v_mfma_f32_16x16x32_bf16 v[84:87], v[148:151], v[204:207], v[84:87]
	v_mfma_f32_16x16x32_bf16 v[80:83], v[156:159], v[204:207], v[80:83]
	v_mfma_f32_16x16x32_bf16 v[68:71], v[148:151], v[212:215], v[68:71]
	v_mfma_f32_16x16x32_bf16 v[64:67], v[156:159], v[212:215], v[64:67]
	s_setprio 0
	s_barrier
	s_add_i32 s46, s71, s6
	s_mov_b32 m0, s46
	ds_read_b128 v[174:177], v183 offset:49152
	ds_read_b128 v[184:187], v183 offset:50176
	ds_read_b128 v[188:191], v183 offset:51200
	ds_read_b128 v[192:195], v183 offset:52224
	ds_read_b128 v[196:199], v183 offset:53248
	ds_read_b128 v[204:207], v183 offset:54272
	ds_read_b128 v[208:211], v183 offset:55296
	ds_read_b128 v[212:215], v183 offset:56320
	global_load_lds_dwordx4 v162, s[98:99]
	s_add_i32 m0, s46, 0x2000
	s_add_u32 s40, s40, 0x40080
	s_addc_u32 s41, s41, 0
	s_add_i32 s46, s72, s6
	global_load_lds_dwordx4 v166, s[98:99]
	s_mov_b32 m0, s46
	s_nop 0
	global_load_lds_dwordx4 v162, s[40:41]
	s_add_i32 m0, s46, 0x2000
	s_nop 0
	global_load_lds_dwordx4 v166, s[40:41]
	s_mov_b32 m0, s61
	s_nop 0
	global_load_lds_dwordx4 v160, s[100:101]
	s_mov_b32 m0, s62
	s_nop 0
	global_load_lds_dwordx4 v164, s[100:101]
	s_waitcnt vmcnt(8)
	s_waitcnt lgkmcnt(0)
	s_barrier
	s_setprio 1
	s_waitcnt lgkmcnt(0)
	v_mfma_f32_16x16x32_bf16 v[60:63], v[128:131], v[174:177], v[60:63]
	v_mfma_f32_16x16x32_bf16 v[56:59], v[136:139], v[174:177], v[56:59]
	v_mfma_f32_16x16x32_bf16 v[44:47], v[128:131], v[188:191], v[44:47]
	v_mfma_f32_16x16x32_bf16 v[40:43], v[136:139], v[188:191], v[40:43]
	v_mfma_f32_16x16x32_bf16 v[28:31], v[128:131], v[196:199], v[28:31]
	v_mfma_f32_16x16x32_bf16 v[24:27], v[136:139], v[196:199], v[24:27]
	v_mfma_f32_16x16x32_bf16 v[12:15], v[128:131], v[208:211], v[12:15]
	v_mfma_f32_16x16x32_bf16 v[8:11], v[136:139], v[208:211], v[8:11]
	v_mfma_f32_16x16x32_bf16 v[60:63], v[132:135], v[184:187], v[60:63]
	v_mfma_f32_16x16x32_bf16 v[56:59], v[140:143], v[184:187], v[56:59]
	v_mfma_f32_16x16x32_bf16 v[44:47], v[132:135], v[192:195], v[44:47]
	v_mfma_f32_16x16x32_bf16 v[40:43], v[140:143], v[192:195], v[40:43]
	v_mfma_f32_16x16x32_bf16 v[28:31], v[132:135], v[204:207], v[28:31]
	v_mfma_f32_16x16x32_bf16 v[24:27], v[140:143], v[204:207], v[24:27]
	v_mfma_f32_16x16x32_bf16 v[12:15], v[132:135], v[212:215], v[12:15]
	v_mfma_f32_16x16x32_bf16 v[8:11], v[140:143], v[212:215], v[8:11]
	s_setprio 0
	s_setprio 1
	v_mfma_f32_16x16x32_bf16 v[52:55], v[144:147], v[174:177], v[52:55]
	v_mfma_f32_16x16x32_bf16 v[48:51], v[152:155], v[174:177], v[48:51]
	v_mfma_f32_16x16x32_bf16 v[36:39], v[144:147], v[188:191], v[36:39]
	v_mfma_f32_16x16x32_bf16 v[32:35], v[152:155], v[188:191], v[32:35]
	v_mfma_f32_16x16x32_bf16 v[20:23], v[144:147], v[196:199], v[20:23]
	v_mfma_f32_16x16x32_bf16 v[16:19], v[152:155], v[196:199], v[16:19]
	v_mfma_f32_16x16x32_bf16 v[4:7], v[144:147], v[208:211], v[4:7]
	v_mfma_f32_16x16x32_bf16 v[0:3], v[152:155], v[208:211], v[0:3]
	v_mfma_f32_16x16x32_bf16 v[52:55], v[148:151], v[184:187], v[52:55]
	v_mfma_f32_16x16x32_bf16 v[48:51], v[156:159], v[184:187], v[48:51]
	v_mfma_f32_16x16x32_bf16 v[36:39], v[148:151], v[192:195], v[36:39]
	v_mfma_f32_16x16x32_bf16 v[32:35], v[156:159], v[192:195], v[32:35]
	v_mfma_f32_16x16x32_bf16 v[20:23], v[148:151], v[204:207], v[20:23]
	v_mfma_f32_16x16x32_bf16 v[16:19], v[156:159], v[204:207], v[16:19]
	v_mfma_f32_16x16x32_bf16 v[4:7], v[148:151], v[212:215], v[4:7]
	v_mfma_f32_16x16x32_bf16 v[0:3], v[156:159], v[212:215], v[0:3]
	s_setprio 0
	s_barrier
	s_add_i32 s70, s70, 2
	s_add_u32 s38, s38, 0x100
	s_addc_u32 s39, s39, 0
	s_add_u32 s68, s68, 0x100
	s_addc_u32 s69, s69, 0
	s_cmp_gt_u32 s70, 13
	s_cbranch_scc0 .LBB0_1378
	s_and_b64 vcc, exec, s[22:23]
	s_cbranch_vccz .LBB0_1381
	s_barrier

; #define PG8_STAGE(bufoff, gbase, voff) do { _Pragma("unroll") for (int _i = 0; _i < 2; ++_i) \
;         __builtin_amdgcn_global_load_lds((const unsigned*)((const char*)(gbase) + (voff)[_i]), (LAS unsigned*)(lds + (bufoff) + ldsw + _i * 8192), 16, 0, 0); } while (0)
; #define PG8_LDA(dst, b, h) do { _Pragma("unroll") for (int m = 0; m < 4; ++m) _Pragma("unroll") for (int k = 0; k < 2; ++k) dst[m][k] = *(const LAS bf16x8*)(lds + PG8_SA(b, h) + aoff + m * 2048 + k * 1024); } while (0)
; #define PG8_LDB(dst, b, h) do { _Pragma("unroll") for (int n = 0; n < 2; ++n) _Pragma("unroll") for (int k = 0; k < 2; ++k) dst[n][k] = *(const LAS bf16x8*)(lds + PG8_SB(b, h) + boff + n * 2048 + k * 1024); } while (0)
; #define PG8_MMA(ai, bj, At, Bt) do { __builtin_amdgcn_s_setprio(1); _Pragma("unroll") for (int m = 0; m < 4; ++m) _Pragma("unroll") for (int n = 0; n < 2; ++n) _Pragma("unroll") for (int k = 0; k < 2; ++k) \
;         acc[ai][bj][m][n] = __builtin_amdgcn_mfma_f32_16x16x32_bf16(Bt[n][k], At[m][k], acc[ai][bj][m][n], 0, 0, 0); __builtin_amdgcn_s_setprio(0); } while (0)
; #define PG8_WAIT_V(n) asm volatile("s_waitcnt vmcnt(" #n ")" ::: "memory")
; #define PG8_WAIT_L(n) asm volatile("s_waitcnt lgkmcnt(" #n ")" ::: "memory")
; #define PG8_BAR __builtin_amdgcn_s_barrier()
; #define PG8_SCHED __builtin_amdgcn_sched_barrier(0)
; template <class Epi, class Sched, bool ALIGN_EPI>
; __device__ __forceinline__ void gemm_phase(LAS unsigned char* lds, const GemmDesc g, const Sched& S, const Epi& E) {
;     ...
;             const bool last = (t == nt - 2);
;             const char* a1 = cA + (size_t)(t + 1) * kstep;
;             const char* a2 = last ? nA : cA + (size_t)(t + 2) * kstep; const char* b2 = last ? nB : cB + (size_t)(t + 2) * kstep;
;             const char* a3 = a2 + kstep; const char* b3 = b2 + kstep;
;             PG8_LDB(B0, 0, 0); PG8_LDB(B1, 0, 1); PG8_SCHED; PG8_LDA(At, 0, 0); PG8_STAGE(PG8_SA(1, 1), a1 + hstepA, voffA);
;             PG8_WAIT_V(8); PG8_WAIT_L(0); PG8_BAR; PG8_MMA(0, 0, At, B0); PG8_MMA(0, 1, At, B1); PG8_BAR; PG8_SCHED;
;             PG8_LDA(At, 0, 1); PG8_STAGE(PG8_SB(0, 0), b2, voffB); PG8_STAGE(PG8_SB(0, 1), b2 + hstepB, voffB); PG8_STAGE(PG8_SA(0, 0), a2, voffA);
;             PG8_WAIT_V(8); PG8_WAIT_L(0); PG8_BAR; PG8_MMA(1, 0, At, B0); PG8_MMA(1, 1, At, B1); PG8_BAR; PG8_SCHED;
.LBB0_1477:
	ds_read_b128 v[80:83], v207
	ds_read_b128 v[84:87], v207 offset:1024
	ds_read_b128 v[88:91], v207 offset:2048
	ds_read_b128 v[92:95], v207 offset:3072
	ds_read_b128 v[96:99], v208
	ds_read_b128 v[100:103], v208 offset:1024
	ds_read_b128 v[104:107], v208 offset:2048
	ds_read_b128 v[108:111], v208 offset:3072
	s_add_u32 s36, s34, 0xfff00080
	s_addc_u32 s37, s35, -1
	s_cmp_eq_u32 s65, 60
	s_cselect_b32 s39, s21, s37
	s_cselect_b32 s38, s23, s36
	s_cselect_b32 s37, s25, s64
	s_cselect_b32 s36, s62, s63
	s_add_i32 m0, s9, 0xc000
	ds_read_b128 v[112:115], v209
	ds_read_b128 v[116:119], v209 offset:1024
	ds_read_b128 v[120:123], v209 offset:2048
	ds_read_b128 v[124:127], v209 offset:3072
	ds_read_b128 v[176:179], v209 offset:4096
	ds_read_b128 v[196:199], v209 offset:5120
	ds_read_b128 v[210:213], v209 offset:6144
	ds_read_b128 v[214:217], v209 offset:7168
	global_load_lds_dwordx4 v188, s[34:35]
	s_add_i32 m0, s9, 0xe000
	s_nop 0
	global_load_lds_dwordx4 v190, s[34:35]
	s_waitcnt vmcnt(8)
	s_waitcnt lgkmcnt(0)
	s_barrier
	s_setprio 1
	s_waitcnt lgkmcnt(0)
	v_mfma_f32_16x16x32_bf16 v[172:175], v[80:83], v[112:115], v[172:175]
	v_mfma_f32_16x16x32_bf16 v[168:171], v[88:91], v[112:115], v[168:171]
	v_mfma_f32_16x16x32_bf16 v[156:159], v[80:83], v[120:123], v[156:159]
	v_mfma_f32_16x16x32_bf16 v[152:155], v[88:91], v[120:123], v[152:155]
	v_mfma_f32_16x16x32_bf16 v[140:143], v[80:83], v[176:179], v[140:143]
	v_mfma_f32_16x16x32_bf16 v[136:139], v[88:91], v[176:179], v[136:139]
	v_mfma_f32_16x16x32_bf16 v[76:79], v[80:83], v[210:213], v[76:79]
	v_mfma_f32_16x16x32_bf16 v[72:75], v[88:91], v[210:213], v[72:75]
	v_mfma_f32_16x16x32_bf16 v[172:175], v[84:87], v[116:119], v[172:175]
	v_mfma_f32_16x16x32_bf16 v[168:171], v[92:95], v[116:119], v[168:171]
	v_mfma_f32_16x16x32_bf16 v[156:159], v[84:87], v[124:127], v[156:159]
	v_mfma_f32_16x16x32_bf16 v[152:155], v[92:95], v[124:127], v[152:155]
	v_mfma_f32_16x16x32_bf16 v[140:143], v[84:87], v[196:199], v[140:143]
	v_mfma_f32_16x16x32_bf16 v[136:139], v[92:95], v[196:199], v[136:139]
	v_mfma_f32_16x16x32_bf16 v[76:79], v[84:87], v[214:217], v[76:79]
	v_mfma_f32_16x16x32_bf16 v[72:75], v[92:95], v[214:217], v[72:75]
	s_setprio 0
	s_setprio 1
	v_mfma_f32_16x16x32_bf16 v[164:167], v[96:99], v[112:115], v[164:167]
	v_mfma_f32_16x16x32_bf16 v[112:115], v[104:107], v[112:115], v[160:163]
	v_mfma_f32_16x16x32_bf16 v[164:167], v[100:103], v[116:119], v[164:167]
	v_mfma_f32_16x16x32_bf16 v[112:115], v[108:111], v[116:119], v[112:115]
	v_mfma_f32_16x16x32_bf16 v[116:119], v[96:99], v[120:123], v[148:151]
	v_mfma_f32_16x16x32_bf16 v[120:123], v[104:107], v[120:123], v[144:147]
	v_mfma_f32_16x16x32_bf16 v[128:131], v[104:107], v[176:179], v[128:131]
	v_mfma_f32_16x16x32_bf16 v[68:71], v[96:99], v[210:213], v[68:71]
	v_mfma_f32_16x16x32_bf16 v[64:67], v[104:107], v[210:213], v[64:67]
	v_mfma_f32_16x16x32_bf16 v[116:119], v[100:103], v[124:127], v[116:119]
	v_mfma_f32_16x16x32_bf16 v[120:123], v[108:111], v[124:127], v[120:123]
	v_mfma_f32_16x16x32_bf16 v[124:127], v[96:99], v[176:179], v[132:135]
	v_mfma_f32_16x16x32_bf16 v[128:131], v[108:111], v[196:199], v[128:131]
	v_mfma_f32_16x16x32_bf16 v[68:71], v[100:103], v[214:217], v[68:71]
	v_mfma_f32_16x16x32_bf16 v[64:67], v[108:111], v[214:217], v[64:67]
	v_mfma_f32_16x16x32_bf16 v[124:127], v[100:103], v[196:199], v[124:127]
	s_setprio 0
	s_barrier
	s_add_i32 s66, s60, s3
	s_add_u32 s98, s36, s10
	s_addc_u32 s99, s37, s11
	s_mov_b32 m0, s66
	ds_read_b128 v[132:135], v209 offset:16384
	ds_read_b128 v[144:147], v209 offset:17408
	ds_read_b128 v[148:151], v209 offset:18432
	ds_read_b128 v[160:163], v209 offset:19456
	ds_read_b128 v[176:179], v209 offset:20480
	ds_read_b128 v[196:199], v209 offset:21504
	ds_read_b128 v[210:213], v209 offset:22528
	ds_read_b128 v[214:217], v209 offset:23552
	global_load_lds_dwordx4 v182, s[36:37]
	s_add_i32 m0, s66, 0x2000
	s_add_u32 s66, s36, 0x100000
	s_addc_u32 s67, s37, 0
	s_add_i32 s68, s61, s3
	global_load_lds_dwordx4 v186, s[36:37]
	s_mov_b32 m0, s68
	s_add_u32 s100, s38, s10
	s_addc_u32 s101, s39, s11
	global_load_lds_dwordx4 v182, s[66:67]
	s_add_i32 m0, s68, 0x2000
	s_nop 0
	global_load_lds_dwordx4 v186, s[66:67]
	s_mov_b32 m0, s9
	s_nop 0
	global_load_lds_dwordx4 v180, s[38:39]
	s_mov_b32 m0, s15
	s_nop 0
	global_load_lds_dwordx4 v184, s[38:39]
	s_waitcnt vmcnt(8)
	s_waitcnt lgkmcnt(0)
	s_barrier
	s_setprio 1
	s_waitcnt lgkmcnt(0)
	v_mfma_f32_16x16x32_bf16 v[60:63], v[80:83], v[132:135], v[60:63]
	v_mfma_f32_16x16x32_bf16 v[56:59], v[88:91], v[132:135], v[56:59]
	v_mfma_f32_16x16x32_bf16 v[44:47], v[80:83], v[148:151], v[44:47]
	v_mfma_f32_16x16x32_bf16 v[40:43], v[88:91], v[148:151], v[40:43]
	v_mfma_f32_16x16x32_bf16 v[28:31], v[80:83], v[176:179], v[28:31]
	v_mfma_f32_16x16x32_bf16 v[24:27], v[88:91], v[176:179], v[24:27]
	v_mfma_f32_16x16x32_bf16 v[12:15], v[80:83], v[210:213], v[12:15]
	v_mfma_f32_16x16x32_bf16 v[8:11], v[88:91], v[210:213], v[8:11]
	v_mfma_f32_16x16x32_bf16 v[60:63], v[84:87], v[144:147], v[60:63]
	v_mfma_f32_16x16x32_bf16 v[56:59], v[92:95], v[144:147], v[56:59]
	v_mfma_f32_16x16x32_bf16 v[44:47], v[84:87], v[160:163], v[44:47]
	v_mfma_f32_16x16x32_bf16 v[40:43], v[92:95], v[160:163], v[40:43]
	v_mfma_f32_16x16x32_bf16 v[28:31], v[84:87], v[196:199], v[28:31]
	v_mfma_f32_16x16x32_bf16 v[24:27], v[92:95], v[196:199], v[24:27]
	v_mfma_f32_16x16x32_bf16 v[12:15], v[84:87], v[214:217], v[12:15]
	v_mfma_f32_16x16x32_bf16 v[8:11], v[92:95], v[214:217], v[8:11]
	s_setprio 0
	s_setprio 1
	v_mfma_f32_16x16x32_bf16 v[52:55], v[96:99], v[132:135], v[52:55]
	v_mfma_f32_16x16x32_bf16 v[48:51], v[104:107], v[132:135], v[48:51]
	v_mfma_f32_16x16x32_bf16 v[36:39], v[96:99], v[148:151], v[36:39]
	v_mfma_f32_16x16x32_bf16 v[32:35], v[104:107], v[148:151], v[32:35]
	v_mfma_f32_16x16x32_bf16 v[20:23], v[96:99], v[176:179], v[20:23]
	v_mfma_f32_16x16x32_bf16 v[16:19], v[104:107], v[176:179], v[16:19]
	v_mfma_f32_16x16x32_bf16 v[4:7], v[96:99], v[210:213], v[4:7]
	v_mfma_f32_16x16x32_bf16 v[0:3], v[104:107], v[210:213], v[0:3]
	v_mfma_f32_16x16x32_bf16 v[52:55], v[100:103], v[144:147], v[52:55]
	v_mfma_f32_16x16x32_bf16 v[48:51], v[108:111], v[144:147], v[48:51]
	v_mfma_f32_16x16x32_bf16 v[36:39], v[100:103], v[160:163], v[36:39]
	v_mfma_f32_16x16x32_bf16 v[32:35], v[108:111], v[160:163], v[32:35]
	v_mfma_f32_16x16x32_bf16 v[20:23], v[100:103], v[196:199], v[20:23]
	v_mfma_f32_16x16x32_bf16 v[16:19], v[108:111], v[196:199], v[16:19]
	v_mfma_f32_16x16x32_bf16 v[4:7], v[100:103], v[214:217], v[4:7]
	v_mfma_f32_16x16x32_bf16 v[0:3], v[108:111], v[214:217], v[0:3]
	s_setprio 0
	s_barrier
; #define PG8_STAGE(bufoff, gbase, voff) do { _Pragma("unroll") for (int _i = 0; _i < 2; ++_i) \
;         __builtin_amdgcn_global_load_lds((const unsigned*)((const char*)(gbase) + (voff)[_i]), (LAS unsigned*)(lds + (bufoff) + ldsw + _i * 8192), 16, 0, 0); } while (0)
; #define PG8_LDA(dst, b, h) do { _Pragma("unroll") for (int m = 0; m < 4; ++m) _Pragma("unroll") for (int k = 0; k < 2; ++k) dst[m][k] = *(const LAS bf16x8*)(lds + PG8_SA(b, h) + aoff + m * 2048 + k * 1024); } while (0)
; #define PG8_LDB(dst, b, h) do { _Pragma("unroll") for (int n = 0; n < 2; ++n) _Pragma("unroll") for (int k = 0; k < 2; ++k) dst[n][k] = *(const LAS bf16x8*)(lds + PG8_SB(b, h) + boff + n * 2048 + k * 1024); } while (0)
; #define PG8_MMA(ai, bj, At, Bt) do { __builtin_amdgcn_s_setprio(1); _Pragma("unroll") for (int m = 0; m < 4; ++m) _Pragma("unroll") for (int n = 0; n < 2; ++n) _Pragma("unroll") for (int k = 0; k < 2; ++k) \
;         acc[ai][bj][m][n] = __builtin_amdgcn_mfma_f32_16x16x32_bf16(Bt[n][k], At[m][k], acc[ai][bj][m][n], 0, 0, 0); __builtin_amdgcn_s_setprio(0); } while (0)
; #define PG8_WAIT_V(n) asm volatile("s_waitcnt vmcnt(" #n ")" ::: "memory")
; #define PG8_WAIT_L(n) asm volatile("s_waitcnt lgkmcnt(" #n ")" ::: "memory")
; #define PG8_BAR __builtin_amdgcn_s_barrier()
; #define PG8_SCHED __builtin_amdgcn_sched_barrier(0)
; template <class Epi, class Sched, bool ALIGN_EPI>
; __device__ __forceinline__ void gemm_phase(LAS unsigned char* lds, const GemmDesc g, const Sched& S, const Epi& E) {
;     ...
;             PG8_LDB(B0, 1, 0); PG8_LDB(B1, 1, 1); PG8_SCHED; PG8_LDA(At, 1, 0); PG8_STAGE(PG8_SA(0, 1), a2 + hstepA, voffA);
;             PG8_WAIT_V(8); PG8_WAIT_L(0); PG8_BAR; PG8_MMA(0, 0, At, B0); PG8_MMA(0, 1, At, B1); PG8_BAR; PG8_SCHED;
;             PG8_LDA(At, 1, 1); PG8_STAGE(PG8_SB(1, 0), b3, voffB); PG8_STAGE(PG8_SB(1, 1), b3 + hstepB, voffB); PG8_STAGE(PG8_SA(1, 0), a3, voffA);
;             PG8_WAIT_V(8); PG8_WAIT_L(0); PG8_BAR; PG8_MMA(1, 0, At, B0); PG8_MMA(1, 1, At, B1); PG8_BAR; PG8_SCHED;
;         }
	s_add_i32 s66, 0, 0x18000
	s_add_i32 s67, 0, 0x1c000
	v_add_u32_e32 v92, s66, v206
	v_add_u32_e32 v108, s67, v206
	ds_read_b128 v[80:83], v92
	ds_read_b128 v[84:87], v92 offset:1024
	ds_read_b128 v[88:91], v92 offset:2048
	ds_read_b128 v[92:95], v92 offset:3072
	ds_read_b128 v[96:99], v108
	ds_read_b128 v[100:103], v108 offset:1024
	ds_read_b128 v[104:107], v108 offset:2048
	ds_read_b128 v[108:111], v108 offset:3072
	s_add_u32 s38, s38, 0x100000
	s_addc_u32 s39, s39, 0
	s_mov_b32 m0, s31
	ds_read_b128 v[132:135], v209 offset:32768
	ds_read_b128 v[144:147], v209 offset:33792
	ds_read_b128 v[176:179], v209 offset:34816
	ds_read_b128 v[196:199], v209 offset:35840
	ds_read_b128 v[210:213], v209 offset:36864
	ds_read_b128 v[214:217], v209 offset:37888
	ds_read_b128 v[218:221], v209 offset:38912
	ds_read_b128 v[222:225], v209 offset:39936
	global_load_lds_dwordx4 v180, s[38:39]
	s_mov_b32 m0, s40
	s_nop 0
	global_load_lds_dwordx4 v184, s[38:39]
	s_waitcnt vmcnt(8)
	s_waitcnt lgkmcnt(0)
	s_barrier
	s_setprio 1
	s_waitcnt lgkmcnt(0)
	v_mfma_f32_16x16x32_bf16 v[148:151], v[80:83], v[132:135], v[172:175]
	v_mfma_f32_16x16x32_bf16 v[172:175], v[84:87], v[144:147], v[148:151]
	v_mfma_f32_16x16x32_bf16 v[148:151], v[88:91], v[132:135], v[168:171]
	v_mfma_f32_16x16x32_bf16 v[168:171], v[92:95], v[144:147], v[148:151]
	v_mfma_f32_16x16x32_bf16 v[148:151], v[80:83], v[176:179], v[156:159]
	v_mfma_f32_16x16x32_bf16 v[156:159], v[84:87], v[196:199], v[148:151]
	v_mfma_f32_16x16x32_bf16 v[148:151], v[88:91], v[176:179], v[152:155]
	v_mfma_f32_16x16x32_bf16 v[140:143], v[80:83], v[210:213], v[140:143]
	v_mfma_f32_16x16x32_bf16 v[136:139], v[88:91], v[210:213], v[136:139]
	v_mfma_f32_16x16x32_bf16 v[76:79], v[80:83], v[218:221], v[76:79]
	v_mfma_f32_16x16x32_bf16 v[72:75], v[88:91], v[218:221], v[72:75]
	v_mfma_f32_16x16x32_bf16 v[152:155], v[92:95], v[196:199], v[148:151]
	v_mfma_f32_16x16x32_bf16 v[140:143], v[84:87], v[214:217], v[140:143]
	v_mfma_f32_16x16x32_bf16 v[136:139], v[92:95], v[214:217], v[136:139]
	v_mfma_f32_16x16x32_bf16 v[76:79], v[84:87], v[222:225], v[76:79]
	v_mfma_f32_16x16x32_bf16 v[72:75], v[92:95], v[222:225], v[72:75]
	s_setprio 0
	s_setprio 1
	v_mfma_f32_16x16x32_bf16 v[112:115], v[104:107], v[132:135], v[112:115]
	v_mfma_f32_16x16x32_bf16 v[148:151], v[96:99], v[132:135], v[164:167]
	v_mfma_f32_16x16x32_bf16 v[160:163], v[108:111], v[144:147], v[112:115]
	v_mfma_f32_16x16x32_bf16 v[112:115], v[96:99], v[176:179], v[116:119]
	v_mfma_f32_16x16x32_bf16 v[164:167], v[100:103], v[144:147], v[148:151]
	v_mfma_f32_16x16x32_bf16 v[148:151], v[100:103], v[196:199], v[112:115]
	v_mfma_f32_16x16x32_bf16 v[112:115], v[104:107], v[176:179], v[120:123]
	v_mfma_f32_16x16x32_bf16 v[144:147], v[108:111], v[196:199], v[112:115]
	v_mfma_f32_16x16x32_bf16 v[112:115], v[96:99], v[210:213], v[124:127]
	v_mfma_f32_16x16x32_bf16 v[132:135], v[100:103], v[214:217], v[112:115]
	v_mfma_f32_16x16x32_bf16 v[112:115], v[104:107], v[210:213], v[128:131]
	v_mfma_f32_16x16x32_bf16 v[68:71], v[96:99], v[218:221], v[68:71]
	v_mfma_f32_16x16x32_bf16 v[64:67], v[104:107], v[218:221], v[64:67]
	v_mfma_f32_16x16x32_bf16 v[128:131], v[108:111], v[214:217], v[112:115]
	v_mfma_f32_16x16x32_bf16 v[68:71], v[100:103], v[222:225], v[68:71]
	v_mfma_f32_16x16x32_bf16 v[64:67], v[108:111], v[222:225], v[64:67]
	s_setprio 0
	s_barrier
	s_add_i32 s38, s66, s3
	s_mov_b32 m0, s38
	ds_read_b128 v[112:115], v209 offset:49152
	ds_read_b128 v[116:119], v209 offset:50176
	ds_read_b128 v[120:123], v209 offset:51200
	ds_read_b128 v[124:127], v209 offset:52224
	ds_read_b128 v[176:179], v209 offset:53248
	ds_read_b128 v[196:199], v209 offset:54272
	ds_read_b128 v[210:213], v209 offset:55296
	ds_read_b128 v[214:217], v209 offset:56320
	global_load_lds_dwordx4 v182, s[98:99]
	s_add_i32 m0, s38, 0x2000
	s_add_u32 s36, s36, 0x100080
	s_addc_u32 s37, s37, 0
	s_add_i32 s38, s67, s3
	global_load_lds_dwordx4 v186, s[98:99]
	s_mov_b32 m0, s38
	s_nop 0
	global_load_lds_dwordx4 v182, s[36:37]
	s_add_i32 m0, s38, 0x2000
	s_nop 0
	global_load_lds_dwordx4 v186, s[36:37]
	s_mov_b32 m0, s46
	s_nop 0
	global_load_lds_dwordx4 v180, s[100:101]
	s_mov_b32 m0, s47
	s_nop 0
	global_load_lds_dwordx4 v184, s[100:101]
	s_waitcnt vmcnt(8)
	s_waitcnt lgkmcnt(0)
	s_barrier
	s_setprio 1
	s_waitcnt lgkmcnt(0)
	v_mfma_f32_16x16x32_bf16 v[60:63], v[80:83], v[112:115], v[60:63]
	v_mfma_f32_16x16x32_bf16 v[56:59], v[88:91], v[112:115], v[56:59]
	v_mfma_f32_16x16x32_bf16 v[44:47], v[80:83], v[120:123], v[44:47]
	v_mfma_f32_16x16x32_bf16 v[40:43], v[88:91], v[120:123], v[40:43]
	v_mfma_f32_16x16x32_bf16 v[28:31], v[80:83], v[176:179], v[28:31]
	v_mfma_f32_16x16x32_bf16 v[24:27], v[88:91], v[176:179], v[24:27]
	v_mfma_f32_16x16x32_bf16 v[12:15], v[80:83], v[210:213], v[12:15]
	v_mfma_f32_16x16x32_bf16 v[8:11], v[88:91], v[210:213], v[8:11]
	v_mfma_f32_16x16x32_bf16 v[60:63], v[84:87], v[116:119], v[60:63]
	v_mfma_f32_16x16x32_bf16 v[56:59], v[92:95], v[116:119], v[56:59]
	v_mfma_f32_16x16x32_bf16 v[44:47], v[84:87], v[124:127], v[44:47]
	v_mfma_f32_16x16x32_bf16 v[40:43], v[92:95], v[124:127], v[40:43]
	v_mfma_f32_16x16x32_bf16 v[28:31], v[84:87], v[196:199], v[28:31]
	v_mfma_f32_16x16x32_bf16 v[24:27], v[92:95], v[196:199], v[24:27]
	v_mfma_f32_16x16x32_bf16 v[12:15], v[84:87], v[214:217], v[12:15]
	v_mfma_f32_16x16x32_bf16 v[8:11], v[92:95], v[214:217], v[8:11]
	s_setprio 0
	s_setprio 1
	v_mfma_f32_16x16x32_bf16 v[52:55], v[96:99], v[112:115], v[52:55]
	v_mfma_f32_16x16x32_bf16 v[48:51], v[104:107], v[112:115], v[48:51]
	v_mfma_f32_16x16x32_bf16 v[36:39], v[96:99], v[120:123], v[36:39]
	v_mfma_f32_16x16x32_bf16 v[32:35], v[104:107], v[120:123], v[32:35]
	v_mfma_f32_16x16x32_bf16 v[20:23], v[96:99], v[176:179], v[20:23]
	v_mfma_f32_16x16x32_bf16 v[16:19], v[104:107], v[176:179], v[16:19]
	v_mfma_f32_16x16x32_bf16 v[4:7], v[96:99], v[210:213], v[4:7]
	v_mfma_f32_16x16x32_bf16 v[0:3], v[104:107], v[210:213], v[0:3]
	v_mfma_f32_16x16x32_bf16 v[52:55], v[100:103], v[116:119], v[52:55]
	v_mfma_f32_16x16x32_bf16 v[48:51], v[108:111], v[116:119], v[48:51]
	v_mfma_f32_16x16x32_bf16 v[36:39], v[100:103], v[124:127], v[36:39]
	v_mfma_f32_16x16x32_bf16 v[32:35], v[108:111], v[124:127], v[32:35]
	v_mfma_f32_16x16x32_bf16 v[20:23], v[100:103], v[196:199], v[20:23]
	v_mfma_f32_16x16x32_bf16 v[16:19], v[108:111], v[196:199], v[16:19]
	v_mfma_f32_16x16x32_bf16 v[4:7], v[100:103], v[214:217], v[4:7]
	v_mfma_f32_16x16x32_bf16 v[0:3], v[108:111], v[214:217], v[0:3]
	s_setprio 0
	s_barrier
	s_add_i32 s65, s65, 2
	s_add_u32 s34, s34, 0x100
	s_addc_u32 s35, s35, 0
	s_add_u32 s63, s63, 0x100
	s_addc_u32 s64, s64, 0
	s_cmp_gt_u32 s65, 61
	s_cbranch_scc0 .LBB0_1477
	s_and_b64 vcc, exec, s[12:13]
	s_cbranch_vccz .LBB0_1480
	s_barrier
